# even in-proj epilogue: 4 serialized rope-table loads per row group hoisted to the group head into distinct regs (one wait instead of four)
# speedup vs baseline: 1.0445x; 1.0111x over previous
.LBB0_1353:
	v_add_u32_e32 v0, s61, v187
	s_waitcnt vmcnt(0)
	ds_read_b128 v[130:133], v0
	ds_read_b128 v[134:137], v0 offset:1024
	ds_read_b128 v[138:141], v0 offset:2048
	ds_read_b128 v[142:145], v0 offset:3072
	s_add_u32 s0, s20, 0xfffc0080
	s_addc_u32 s1, s21, -1
	s_cmp_eq_u32 s26, 12
	s_cselect_b32 s43, s4, s1
	s_cselect_b32 s42, s8, s0
	s_cselect_b32 s35, s10, s25
	s_cselect_b32 s34, s11, s24
	v_lshl_add_u64 v[194:195], s[20:21], 0, v[174:175]
	s_add_i32 m0, s67, 0xc000
	ds_read_b128 v[146:149], v202
	ds_read_b128 v[150:153], v202 offset:1024
	ds_read_b128 v[154:157], v202 offset:2048
	ds_read_b128 v[158:161], v202 offset:3072
	ds_read_b128 v[178:181], v202 offset:4096
	ds_read_b128 v[182:185], v202 offset:5120
	ds_read_b128 v[204:207], v202 offset:6144
	ds_read_b128 v[208:211], v202 offset:7168
	global_load_lds_dwordx4 v[194:195], off
	v_lshl_add_u64 v[194:195], s[20:21], 0, v[176:177]
	s_add_i32 m0, s67, 0xe000
	s_nop 0
	global_load_lds_dwordx4 v[194:195], off
	s_waitcnt lgkmcnt(8)
	s_barrier
	s_waitcnt lgkmcnt(0)
	s_setprio 1
	s_waitcnt lgkmcnt(0)
	v_mfma_f32_16x16x32_bf16 v[126:129], v[130:133], v[146:149], v[126:129]
	v_mfma_f32_16x16x32_bf16 v[122:125], v[138:141], v[146:149], v[122:125]
	v_mfma_f32_16x16x32_bf16 v[118:121], v[130:133], v[154:157], v[118:121]
	v_mfma_f32_16x16x32_bf16 v[114:117], v[138:141], v[154:157], v[114:117]
	v_mfma_f32_16x16x32_bf16 v[102:105], v[130:133], v[178:181], v[102:105]
	v_mfma_f32_16x16x32_bf16 v[98:101], v[138:141], v[178:181], v[98:101]
	v_mfma_f32_16x16x32_bf16 v[86:89], v[130:133], v[204:207], v[86:89]
	v_mfma_f32_16x16x32_bf16 v[82:85], v[138:141], v[204:207], v[82:85]
	v_mfma_f32_16x16x32_bf16 v[126:129], v[134:137], v[150:153], v[126:129]
	v_mfma_f32_16x16x32_bf16 v[122:125], v[142:145], v[150:153], v[122:125]
	v_mfma_f32_16x16x32_bf16 v[118:121], v[134:137], v[158:161], v[118:121]
	v_mfma_f32_16x16x32_bf16 v[114:117], v[142:145], v[158:161], v[114:117]
	v_mfma_f32_16x16x32_bf16 v[102:105], v[134:137], v[182:185], v[102:105]
	v_mfma_f32_16x16x32_bf16 v[98:101], v[142:145], v[182:185], v[98:101]
	v_mfma_f32_16x16x32_bf16 v[86:89], v[134:137], v[208:211], v[86:89]
	v_mfma_f32_16x16x32_bf16 v[82:85], v[142:145], v[208:211], v[82:85]
	s_setprio 0
	s_barrier
	s_mov_b32 m0, s62
	v_add_u32_e32 v0, s78, v187
	v_lshl_add_u64 v[194:195], s[34:35], 0, v[162:163]
	ds_read_b128 v[212:215], v0
	ds_read_b128 v[216:219], v0 offset:1024
	ds_read_b128 v[220:223], v0 offset:2048
	ds_read_b128 v[242:245], v0 offset:3072
	global_load_lds_dwordx4 v[194:195], off
	v_lshl_add_u64 v[196:197], s[34:35], 0, v[164:165]
	s_mov_b32 m0, s63
	s_nop 0
	global_load_lds_dwordx4 v[196:197], off
	s_barrier
	s_waitcnt lgkmcnt(0)
	s_setprio 1
	s_waitcnt lgkmcnt(0)
	v_mfma_f32_16x16x32_bf16 v[110:113], v[212:215], v[146:149], v[110:113]
	v_mfma_f32_16x16x32_bf16 v[106:109], v[220:223], v[146:149], v[106:109]
	v_mfma_f32_16x16x32_bf16 v[94:97], v[212:215], v[154:157], v[94:97]
	v_mfma_f32_16x16x32_bf16 v[90:93], v[220:223], v[154:157], v[90:93]
	v_mfma_f32_16x16x32_bf16 v[78:81], v[212:215], v[178:181], v[78:81]
	v_mfma_f32_16x16x32_bf16 v[74:77], v[220:223], v[178:181], v[74:77]
	v_mfma_f32_16x16x32_bf16 v[70:73], v[212:215], v[204:207], v[70:73]
	v_mfma_f32_16x16x32_bf16 v[66:69], v[220:223], v[204:207], v[66:69]
	v_mfma_f32_16x16x32_bf16 v[110:113], v[216:219], v[150:153], v[110:113]
	v_mfma_f32_16x16x32_bf16 v[106:109], v[242:245], v[150:153], v[106:109]
	v_mfma_f32_16x16x32_bf16 v[94:97], v[216:219], v[158:161], v[94:97]
	v_mfma_f32_16x16x32_bf16 v[90:93], v[242:245], v[158:161], v[90:93]
	v_mfma_f32_16x16x32_bf16 v[78:81], v[216:219], v[182:185], v[78:81]
	v_mfma_f32_16x16x32_bf16 v[74:77], v[242:245], v[182:185], v[74:77]
	v_mfma_f32_16x16x32_bf16 v[70:73], v[216:219], v[208:211], v[70:73]
	v_mfma_f32_16x16x32_bf16 v[66:69], v[242:245], v[208:211], v[66:69]
	s_setprio 0
	s_mov_b32 m0, s67
	v_lshl_add_u64 v[246:247], s[42:43], 0, v[162:163]
	s_barrier
	ds_read_b128 v[146:149], v202 offset:16384
	ds_read_b128 v[150:153], v202 offset:17408
	ds_read_b128 v[154:157], v202 offset:18432
	ds_read_b128 v[158:161], v202 offset:19456
	ds_read_b128 v[178:181], v202 offset:20480
	ds_read_b128 v[182:185], v202 offset:21504
	ds_read_b128 v[204:207], v202 offset:22528
	ds_read_b128 v[208:211], v202 offset:23552
	global_load_lds_dwordx4 v[246:247], off
	v_lshl_add_u64 v[248:249], s[42:43], 0, v[164:165]
	s_mov_b32 m0, s75
	s_nop 0
	global_load_lds_dwordx4 v[248:249], off
	s_barrier
	s_waitcnt lgkmcnt(0)
	s_setprio 1
	s_waitcnt lgkmcnt(0)
	v_mfma_f32_16x16x32_bf16 v[62:65], v[130:133], v[146:149], v[62:65]
	v_mfma_f32_16x16x32_bf16 v[58:61], v[138:141], v[146:149], v[58:61]
	v_mfma_f32_16x16x32_bf16 v[54:57], v[130:133], v[154:157], v[54:57]
	v_mfma_f32_16x16x32_bf16 v[50:53], v[138:141], v[154:157], v[50:53]
	v_mfma_f32_16x16x32_bf16 v[38:41], v[130:133], v[178:181], v[38:41]
	v_mfma_f32_16x16x32_bf16 v[34:37], v[138:141], v[178:181], v[34:37]
	v_mfma_f32_16x16x32_bf16 v[22:25], v[130:133], v[204:207], v[22:25]
	v_mfma_f32_16x16x32_bf16 v[14:17], v[138:141], v[204:207], v[14:17]
	v_mfma_f32_16x16x32_bf16 v[62:65], v[134:137], v[150:153], v[62:65]
	v_mfma_f32_16x16x32_bf16 v[58:61], v[142:145], v[150:153], v[58:61]
	v_mfma_f32_16x16x32_bf16 v[54:57], v[134:137], v[158:161], v[54:57]
	v_mfma_f32_16x16x32_bf16 v[50:53], v[142:145], v[158:161], v[50:53]
	v_mfma_f32_16x16x32_bf16 v[38:41], v[134:137], v[182:185], v[38:41]
	v_mfma_f32_16x16x32_bf16 v[34:37], v[142:145], v[182:185], v[34:37]
	v_mfma_f32_16x16x32_bf16 v[22:25], v[134:137], v[208:211], v[22:25]
	v_mfma_f32_16x16x32_bf16 v[14:17], v[142:145], v[208:211], v[14:17]
	s_setprio 0
	s_barrier
	s_add_u32 s0, s34, 0x40000
	s_addc_u32 s1, s35, 0
	s_mov_b32 m0, s79
	v_lshl_add_u64 v[130:131], s[0:1], 0, v[162:163]
	global_load_lds_dwordx4 v[130:131], off
	v_lshl_add_u64 v[130:131], s[0:1], 0, v[164:165]
	s_mov_b32 m0, s92
	s_nop 0
	global_load_lds_dwordx4 v[130:131], off
	s_waitcnt vmcnt(6)
	s_barrier
	s_setprio 1
	v_mfma_f32_16x16x32_bf16 v[46:49], v[212:215], v[146:149], v[46:49]
	v_mfma_f32_16x16x32_bf16 v[42:45], v[220:223], v[146:149], v[42:45]
	v_mfma_f32_16x16x32_bf16 v[30:33], v[212:215], v[154:157], v[30:33]
	v_mfma_f32_16x16x32_bf16 v[26:29], v[220:223], v[154:157], v[26:29]
	v_mfma_f32_16x16x32_bf16 v[18:21], v[212:215], v[178:181], v[18:21]
	v_mfma_f32_16x16x32_bf16 v[10:13], v[220:223], v[178:181], v[10:13]
	v_mfma_f32_16x16x32_bf16 v[6:9], v[212:215], v[204:207], v[6:9]
	v_mfma_f32_16x16x32_bf16 v[2:5], v[220:223], v[204:207], v[2:5]
	v_mfma_f32_16x16x32_bf16 v[46:49], v[216:219], v[150:153], v[46:49]
	v_mfma_f32_16x16x32_bf16 v[42:45], v[242:245], v[150:153], v[42:45]
	v_mfma_f32_16x16x32_bf16 v[30:33], v[216:219], v[158:161], v[30:33]
	v_mfma_f32_16x16x32_bf16 v[26:29], v[242:245], v[158:161], v[26:29]
	v_mfma_f32_16x16x32_bf16 v[18:21], v[216:219], v[182:185], v[18:21]
	v_mfma_f32_16x16x32_bf16 v[10:13], v[242:245], v[182:185], v[10:13]
	v_mfma_f32_16x16x32_bf16 v[6:9], v[216:219], v[208:211], v[6:9]
	v_mfma_f32_16x16x32_bf16 v[2:5], v[242:245], v[208:211], v[2:5]
	s_setprio 0
	v_add_u32_e32 v0, s80, v187
	s_barrier
	ds_read_b128 v[130:133], v0
	ds_read_b128 v[134:137], v0 offset:1024
	ds_read_b128 v[138:141], v0 offset:2048
	ds_read_b128 v[142:145], v0 offset:3072
	s_add_u32 s0, s42, 0x40000
	s_addc_u32 s1, s43, 0
	s_mov_b32 m0, s93
	v_lshl_add_u64 v[212:213], s[0:1], 0, v[162:163]
	ds_read_b128 v[146:149], v202 offset:32768
	ds_read_b128 v[150:153], v202 offset:33792
	ds_read_b128 v[154:157], v202 offset:34816
	ds_read_b128 v[158:161], v202 offset:35840
	ds_read_b128 v[178:181], v202 offset:36864
	ds_read_b128 v[182:185], v202 offset:37888
	ds_read_b128 v[204:207], v202 offset:38912
	ds_read_b128 v[208:211], v202 offset:39936
	global_load_lds_dwordx4 v[212:213], off
	v_lshl_add_u64 v[212:213], s[0:1], 0, v[164:165]
	s_mov_b32 m0, s60
	s_nop 0
	global_load_lds_dwordx4 v[212:213], off
	s_waitcnt lgkmcnt(8)
	s_barrier
	s_waitcnt lgkmcnt(0)
	s_setprio 1
	s_waitcnt lgkmcnt(0)
	v_mfma_f32_16x16x32_bf16 v[126:129], v[130:133], v[146:149], v[126:129]
	v_mfma_f32_16x16x32_bf16 v[122:125], v[138:141], v[146:149], v[122:125]
	v_mfma_f32_16x16x32_bf16 v[118:121], v[130:133], v[154:157], v[118:121]
	v_mfma_f32_16x16x32_bf16 v[114:117], v[138:141], v[154:157], v[114:117]
	v_mfma_f32_16x16x32_bf16 v[102:105], v[130:133], v[178:181], v[102:105]
	v_mfma_f32_16x16x32_bf16 v[98:101], v[138:141], v[178:181], v[98:101]
	v_mfma_f32_16x16x32_bf16 v[86:89], v[130:133], v[204:207], v[86:89]
	v_mfma_f32_16x16x32_bf16 v[82:85], v[138:141], v[204:207], v[82:85]
	v_mfma_f32_16x16x32_bf16 v[126:129], v[134:137], v[150:153], v[126:129]
	v_mfma_f32_16x16x32_bf16 v[122:125], v[142:145], v[150:153], v[122:125]
	v_mfma_f32_16x16x32_bf16 v[118:121], v[134:137], v[158:161], v[118:121]
	v_mfma_f32_16x16x32_bf16 v[114:117], v[142:145], v[158:161], v[114:117]
	v_mfma_f32_16x16x32_bf16 v[102:105], v[134:137], v[182:185], v[102:105]
	v_mfma_f32_16x16x32_bf16 v[98:101], v[142:145], v[182:185], v[98:101]
	v_mfma_f32_16x16x32_bf16 v[86:89], v[134:137], v[208:211], v[86:89]
	v_mfma_f32_16x16x32_bf16 v[82:85], v[142:145], v[208:211], v[82:85]
	s_setprio 0
	s_barrier
	s_mov_b32 m0, s81
	v_add_u32_e32 v0, s14, v187
	v_lshl_add_u64 v[194:195], v[194:195], 0, s[88:89]
	ds_read_b128 v[212:215], v0
	ds_read_b128 v[216:219], v0 offset:1024
	ds_read_b128 v[220:223], v0 offset:2048
	ds_read_b128 v[242:245], v0 offset:3072
	global_load_lds_dwordx4 v[194:195], off
	v_lshl_add_u64 v[194:195], v[196:197], 0, s[88:89]
	s_mov_b32 m0, s68
	s_nop 0
	global_load_lds_dwordx4 v[194:195], off
	s_barrier
	s_waitcnt lgkmcnt(0)
	s_setprio 1
	s_waitcnt lgkmcnt(0)
	v_mfma_f32_16x16x32_bf16 v[110:113], v[212:215], v[146:149], v[110:113]
	v_mfma_f32_16x16x32_bf16 v[106:109], v[220:223], v[146:149], v[106:109]
	v_mfma_f32_16x16x32_bf16 v[94:97], v[212:215], v[154:157], v[94:97]
	v_mfma_f32_16x16x32_bf16 v[90:93], v[220:223], v[154:157], v[90:93]
	v_mfma_f32_16x16x32_bf16 v[78:81], v[212:215], v[178:181], v[78:81]
	v_mfma_f32_16x16x32_bf16 v[74:77], v[220:223], v[178:181], v[74:77]
	v_mfma_f32_16x16x32_bf16 v[70:73], v[212:215], v[204:207], v[70:73]
	v_mfma_f32_16x16x32_bf16 v[66:69], v[220:223], v[204:207], v[66:69]
	v_mfma_f32_16x16x32_bf16 v[110:113], v[216:219], v[150:153], v[110:113]
	v_mfma_f32_16x16x32_bf16 v[106:109], v[242:245], v[150:153], v[106:109]
	v_mfma_f32_16x16x32_bf16 v[94:97], v[216:219], v[158:161], v[94:97]
	v_mfma_f32_16x16x32_bf16 v[90:93], v[242:245], v[158:161], v[90:93]
	v_mfma_f32_16x16x32_bf16 v[78:81], v[216:219], v[182:185], v[78:81]
	v_mfma_f32_16x16x32_bf16 v[74:77], v[242:245], v[182:185], v[74:77]
	v_mfma_f32_16x16x32_bf16 v[70:73], v[216:219], v[208:211], v[70:73]
	v_mfma_f32_16x16x32_bf16 v[66:69], v[242:245], v[208:211], v[66:69]
	s_setprio 0
	s_mov_b32 m0, s69
	v_lshl_add_u64 v[194:195], v[246:247], 0, s[88:89]
	s_barrier
	ds_read_b128 v[146:149], v202 offset:49152
	ds_read_b128 v[150:153], v202 offset:50176
	ds_read_b128 v[154:157], v202 offset:51200
	ds_read_b128 v[158:161], v202 offset:52224
	ds_read_b128 v[178:181], v202 offset:53248
	ds_read_b128 v[182:185], v202 offset:54272
	ds_read_b128 v[204:207], v202 offset:55296
	ds_read_b128 v[208:211], v202 offset:56320
	global_load_lds_dwordx4 v[194:195], off
	v_lshl_add_u64 v[194:195], v[248:249], 0, s[88:89]
	s_mov_b32 m0, s19
	s_nop 0
	global_load_lds_dwordx4 v[194:195], off
	s_barrier
	s_waitcnt lgkmcnt(0)
	s_setprio 1
	s_waitcnt lgkmcnt(0)
	v_mfma_f32_16x16x32_bf16 v[62:65], v[130:133], v[146:149], v[62:65]
	v_mfma_f32_16x16x32_bf16 v[58:61], v[138:141], v[146:149], v[58:61]
	v_mfma_f32_16x16x32_bf16 v[54:57], v[130:133], v[154:157], v[54:57]
	v_mfma_f32_16x16x32_bf16 v[50:53], v[138:141], v[154:157], v[50:53]
	v_mfma_f32_16x16x32_bf16 v[38:41], v[130:133], v[178:181], v[38:41]
	v_mfma_f32_16x16x32_bf16 v[34:37], v[138:141], v[178:181], v[34:37]
	v_mfma_f32_16x16x32_bf16 v[22:25], v[130:133], v[204:207], v[22:25]
	v_mfma_f32_16x16x32_bf16 v[14:17], v[138:141], v[204:207], v[14:17]
	v_mfma_f32_16x16x32_bf16 v[62:65], v[134:137], v[150:153], v[62:65]
	v_mfma_f32_16x16x32_bf16 v[58:61], v[142:145], v[150:153], v[58:61]
	v_mfma_f32_16x16x32_bf16 v[54:57], v[134:137], v[158:161], v[54:57]
	v_mfma_f32_16x16x32_bf16 v[50:53], v[142:145], v[158:161], v[50:53]
	v_mfma_f32_16x16x32_bf16 v[38:41], v[134:137], v[182:185], v[38:41]
	v_mfma_f32_16x16x32_bf16 v[34:37], v[142:145], v[182:185], v[34:37]
	v_mfma_f32_16x16x32_bf16 v[22:25], v[134:137], v[208:211], v[22:25]
	v_mfma_f32_16x16x32_bf16 v[14:17], v[142:145], v[208:211], v[14:17]
	s_setprio 0
	s_barrier
	s_add_u32 s0, s34, 0x40080
	s_addc_u32 s1, s35, 0
	s_mov_b32 m0, s15
	v_lshl_add_u64 v[130:131], s[0:1], 0, v[162:163]
	global_load_lds_dwordx4 v[130:131], off
	v_lshl_add_u64 v[130:131], s[0:1], 0, v[164:165]
	s_mov_b32 m0, s16
	s_nop 0
	global_load_lds_dwordx4 v[130:131], off
	s_waitcnt vmcnt(6)
	s_barrier
	s_setprio 1
	v_mfma_f32_16x16x32_bf16 v[46:49], v[212:215], v[146:149], v[46:49]
	v_mfma_f32_16x16x32_bf16 v[42:45], v[220:223], v[146:149], v[42:45]
	v_mfma_f32_16x16x32_bf16 v[30:33], v[212:215], v[154:157], v[30:33]
	v_mfma_f32_16x16x32_bf16 v[26:29], v[220:223], v[154:157], v[26:29]
	v_mfma_f32_16x16x32_bf16 v[18:21], v[212:215], v[178:181], v[18:21]
	v_mfma_f32_16x16x32_bf16 v[10:13], v[220:223], v[178:181], v[10:13]
	v_mfma_f32_16x16x32_bf16 v[6:9], v[212:215], v[204:207], v[6:9]
	v_mfma_f32_16x16x32_bf16 v[2:5], v[220:223], v[204:207], v[2:5]
	v_mfma_f32_16x16x32_bf16 v[46:49], v[216:219], v[150:153], v[46:49]
	v_mfma_f32_16x16x32_bf16 v[42:45], v[242:245], v[150:153], v[42:45]
	v_mfma_f32_16x16x32_bf16 v[30:33], v[216:219], v[158:161], v[30:33]
	v_mfma_f32_16x16x32_bf16 v[26:29], v[242:245], v[158:161], v[26:29]
	v_mfma_f32_16x16x32_bf16 v[18:21], v[216:219], v[182:185], v[18:21]
	v_mfma_f32_16x16x32_bf16 v[10:13], v[242:245], v[182:185], v[10:13]
	v_mfma_f32_16x16x32_bf16 v[6:9], v[216:219], v[208:211], v[6:9]
	v_mfma_f32_16x16x32_bf16 v[2:5], v[242:245], v[208:211], v[2:5]
	s_setprio 0
	s_add_i32 s26, s26, 2
	s_add_u32 s20, s20, 0x100
	s_addc_u32 s21, s21, 0
	s_add_u32 s24, s24, 0x100
	s_addc_u32 s25, s25, 0
	s_cmp_gt_u32 s26, 13
	s_barrier
	s_cbranch_scc0 .LBB0_1353
	s_cmp_lt_i32 s66, 3
	s_mov_b64 s[20:21], -1
	s_cbranch_scc0 .LBB0_1556
	s_cmp_lg_u32 s66, 2
	s_cselect_b64 s[34:35], -1, 0
	s_cmp_eq_u32 s66, 2
	s_mov_b32 s24, s45
	s_mov_b32 s18, s44
	s_cselect_b64 s[0:1], -1, 0
	v_readlane_b32 s44, v254, 5
	s_and_b64 s[10:11], s[0:1], exec
	v_readlane_b32 s46, v254, 7
	v_readlane_b32 s45, v254, 6
	v_readlane_b32 s47, v254, 8
	s_cselect_b32 s8, s46, s44
	s_cselect_b32 s4, s47, s45
	s_add_u32 s10, s8, s2
	s_addc_u32 s11, s4, s3
	v_lshlrev_b32_e32 v178, 2, v166
	global_load_dwordx4 v[138:141], v178, s[10:11] offset:16
	global_load_dwordx4 v[142:145], v178, s[10:11]
	global_load_dwordx4 v[130:133], v178, s[10:11] offset:144
	global_load_dwordx4 v[134:137], v178, s[10:11] offset:128
	v_readlane_b32 s10, v254, 26
	s_lshl_b32 s26, s74, 8
	v_readlane_b32 s11, v254, 27
	s_add_i32 s26, s26, s30
	s_and_b64 s[20:21], s[0:1], s[10:11]
	v_or_b32_e32 v180, s26, v167
	v_mov_b64_e32 v[148:149], v[128:129]
	v_mov_b64_e32 v[152:153], v[124:125]
	v_mov_b64_e32 v[156:157], v[112:113]
	v_cmp_lt_i32_e64 s[42:43], s29, v180
	v_cmp_gt_i32_e64 s[46:47], s33, v180
	v_bitop3_b32 v182, s26, v231, v167 bitop3:0xc8
	s_and_b64 vcc, exec, s[20:21]
	v_xor_b32_e32 v205, 16, v224
	v_add_u32_e32 v203, 64, v225
	v_xor_b32_e32 v204, 32, v224
	v_mov_b32_e32 v161, v109
	v_mov_b32_e32 v160, v108
	v_mov_b32_e32 v159, v107
	v_mov_b32_e32 v158, v106
	v_mov_b64_e32 v[146:147], v[126:127]
	v_mov_b64_e32 v[150:151], v[122:123]
	v_mov_b64_e32 v[154:155], v[110:111]
	s_cbranch_vccnz .LBB0_1365
	v_lshl_or_b32 v222, v182, 6, v166
	v_lshlrev_b32_e32 v222, 2, v222
	s_and_saveexec_b64 vcc, s[42:43]
	s_cbranch_execz .Lrope_skip_0
	global_load_dwordx4 v[214:217], v222, s[84:85]
	global_load_dwordx4 v[218:221], v222, s[84:85] offset:16
	global_load_dwordx4 v[242:245], v222, s[84:85] offset:128
	global_load_dwordx4 v[246:249], v222, s[84:85] offset:144
.Lrope_skip_0:
	s_or_b64 exec, exec, vcc
	v_mul_f32_e32 v0, v127, v127
	v_fmac_f32_e32 v0, v126, v126
	v_fmac_f32_e32 v0, v128, v128
	v_fmac_f32_e32 v0, v129, v129
	v_fmac_f32_e32 v0, v122, v122
	v_fmac_f32_e32 v0, v123, v123
	v_fmac_f32_e32 v0, v124, v124
	v_fmac_f32_e32 v0, v125, v125
	v_pk_mul_f32 v[148:149], v[110:111], v[110:111]
	v_pk_mul_f32 v[146:147], v[112:113], v[112:113]
	v_add_f32_e32 v0, v148, v0
	v_add_f32_e32 v0, v149, v0
	v_add_f32_e32 v0, v146, v0
	v_add_f32_e32 v0, v147, v0
	v_pk_mul_f32 v[148:149], v[106:107], v[106:107]
	v_pk_mul_f32 v[146:147], v[108:109], v[108:109]
	v_add_f32_e32 v0, v148, v0
	v_add_f32_e32 v0, v149, v0
	v_cmp_lt_i32_e32 vcc, v205, v203
	v_add_f32_e32 v0, v146, v0
	v_add_f32_e32 v0, v147, v0
	v_cndmask_b32_e32 v146, v224, v205, vcc
	v_lshlrev_b32_e32 v146, 2, v146
	ds_bpermute_b32 v146, v146, v0
	v_cmp_lt_i32_e32 vcc, v204, v203
	s_waitcnt lgkmcnt(0)
	v_add_f32_e32 v0, v0, v146
	v_cndmask_b32_e32 v146, v224, v204, vcc
	v_lshlrev_b32_e32 v146, 2, v146
	ds_bpermute_b32 v146, v146, v0
	s_waitcnt lgkmcnt(0)
	v_add_f32_e32 v0, v0, v146
	v_fmamk_f32 v0, v0, 0x3c800000, v226
	v_mul_f32_e32 v146, 0x4b800000, v0
	v_cmp_gt_f32_e32 vcc, s58, v0
	s_nop 1
	v_cndmask_b32_e32 v0, v0, v146, vcc
	v_rsq_f32_e32 v0, v0
	s_nop 0
	v_mul_f32_e32 v146, 0x45800000, v0
	v_cndmask_b32_e32 v158, v0, v146, vcc
	v_lshl_or_b32 v0, v182, 6, v166
	v_pk_mul_f32 v[146:147], v[126:127], v[158:159] op_sel_hi:[1,0]
	v_pk_mul_f32 v[148:149], v[128:129], v[158:159] op_sel_hi:[1,0]
	s_waitcnt vmcnt(0)
	v_pk_mul_f32 v[146:147], v[142:143], v[146:147]
	v_pk_mul_f32 v[148:149], v[144:145], v[148:149]
	v_lshlrev_b32_e32 v0, 2, v0
	s_and_saveexec_b64 s[44:45], s[42:43]
	s_cbranch_execz .LBB0_1358
	v_pk_mul_f32 v[156:157], v[146:147], v[214:215] op_sel:[1,1] op_sel_hi:[1,0]
	s_nop 0
	v_pk_fma_f32 v[154:155], v[146:147], v[214:215], v[156:157] op_sel_hi:[0,1,1] neg_lo:[0,0,1] neg_hi:[0,0,1]
	v_pk_fma_f32 v[146:147], v[146:147], v[214:215], v[156:157] op_sel_hi:[0,1,1]
	v_mul_f32_e32 v146, v149, v217
	v_pk_fma_f32 v[156:157], v[148:149], v[216:217], v[146:147] op_sel_hi:[1,1,0] neg_lo:[0,0,1] neg_hi:[0,0,1]
	v_mul_f32_e32 v146, v149, v216
	v_pk_fma_f32 v[148:149], v[148:149], v[216:217], v[146:147] op_sel:[0,1,0] op_sel_hi:[1,0,0]
	v_mov_b32_e32 v155, v147
	v_mov_b32_e32 v157, v148
	v_mov_b64_e32 v[146:147], v[154:155]
	v_mov_b64_e32 v[148:149], v[156:157]
.LBB0_1358:
	s_or_b64 exec, exec, s[44:45]
	v_mov_b32_e32 v159, v158
	v_mov_b32_e32 v154, v158
	v_mov_b32_e32 v155, v158
	v_pk_mul_f32 v[150:151], v[124:125], v[154:155]
	v_pk_mul_f32 v[156:157], v[122:123], v[158:159]
	v_pk_mul_f32 v[152:153], v[140:141], v[150:151]
	v_pk_mul_f32 v[150:151], v[138:139], v[156:157]
	s_and_saveexec_b64 s[44:45], s[42:43]
	s_cbranch_execz .LBB0_1360
	v_pk_mul_f32 v[156:157], v[150:151], v[218:219] op_sel:[1,1] op_sel_hi:[1,0]
	s_nop 0
	v_pk_fma_f32 v[210:211], v[150:151], v[218:219], v[156:157] op_sel_hi:[0,1,1] neg_lo:[0,0,1] neg_hi:[0,0,1]
	v_pk_fma_f32 v[150:151], v[150:151], v[218:219], v[156:157] op_sel_hi:[0,1,1]
	v_mul_f32_e32 v150, v153, v221
	v_pk_fma_f32 v[212:213], v[152:153], v[220:221], v[150:151] op_sel_hi:[1,1,0] neg_lo:[0,0,1] neg_hi:[0,0,1]
	v_mul_f32_e32 v150, v153, v220
	v_pk_fma_f32 v[152:153], v[152:153], v[220:221], v[150:151] op_sel:[0,1,0] op_sel_hi:[1,0,0]
	v_mov_b32_e32 v211, v151
	v_mov_b32_e32 v213, v152
	v_mov_b64_e32 v[150:151], v[210:211]
	v_mov_b64_e32 v[152:153], v[212:213]
.LBB0_1360:
	s_or_b64 exec, exec, s[44:45]
	v_pk_mul_f32 v[154:155], v[112:113], v[154:155]
	v_pk_mul_f32 v[160:161], v[110:111], v[158:159]
	v_pk_mul_f32 v[156:157], v[136:137], v[154:155]
	v_pk_mul_f32 v[154:155], v[134:135], v[160:161]
	s_and_saveexec_b64 s[44:45], s[42:43]
	s_cbranch_execz .LBB0_1362
	v_pk_mul_f32 v[160:161], v[154:155], v[242:243] op_sel:[1,1] op_sel_hi:[1,0]
	s_nop 0
	v_pk_fma_f32 v[210:211], v[154:155], v[242:243], v[160:161] op_sel_hi:[0,1,1] neg_lo:[0,0,1] neg_hi:[0,0,1]
	v_pk_fma_f32 v[154:155], v[154:155], v[242:243], v[160:161] op_sel_hi:[0,1,1]
	v_mul_f32_e32 v154, v157, v245
	v_pk_fma_f32 v[212:213], v[156:157], v[244:245], v[154:155] op_sel_hi:[1,1,0] neg_lo:[0,0,1] neg_hi:[0,0,1]
	v_mul_f32_e32 v154, v157, v244
	v_pk_fma_f32 v[156:157], v[156:157], v[244:245], v[154:155] op_sel:[0,1,0] op_sel_hi:[1,0,0]
	v_mov_b32_e32 v211, v155
	v_mov_b32_e32 v213, v156
	v_mov_b64_e32 v[154:155], v[210:211]
	v_mov_b64_e32 v[156:157], v[212:213]
.LBB0_1362:
	s_or_b64 exec, exec, s[44:45]
	v_mov_b32_e32 v160, v158
	v_mov_b32_e32 v161, v158
	v_pk_mul_f32 v[160:161], v[108:109], v[160:161]
	v_pk_mul_f32 v[158:159], v[106:107], v[158:159]
	v_pk_mul_f32 v[160:161], v[132:133], v[160:161]
	v_pk_mul_f32 v[158:159], v[130:131], v[158:159]
	s_and_saveexec_b64 s[44:45], s[42:43]
	s_cbranch_execz .LBB0_1364
	v_mul_f32_e32 v0, v161, v249
	v_pk_mul_f32 v[194:195], v[158:159], v[246:247] op_sel:[1,1] op_sel_hi:[1,0]
	v_pk_fma_f32 v[196:197], v[160:161], v[248:249], v[0:1] op_sel_hi:[1,1,0] neg_lo:[0,0,1] neg_hi:[0,0,1]
	v_mul_f32_e32 v0, v161, v248
	v_pk_mul_f32 v[184:185], v[158:159], v[246:247]
	v_pk_fma_f32 v[158:159], v[158:159], v[246:247], v[194:195] op_sel_hi:[0,1,1]
	v_pk_fma_f32 v[160:161], v[160:161], v[248:249], v[0:1] op_sel:[0,1,0] op_sel_hi:[1,0,0]
	v_sub_f32_e32 v158, v184, v194
	v_mov_b32_e32 v161, v160
	v_mov_b32_e32 v160, v196

.LBB0_1380:
	v_or_b32_e32 v184, 16, v180
	s_movk_i32 s0, 0x7df
	v_cndmask_b32_e64 v0, 0, 1, s[20:21]
	v_mov_b64_e32 v[148:149], v[120:121]
	v_mov_b64_e32 v[152:153], v[116:117]
	v_mov_b64_e32 v[156:157], v[96:97]
	v_cmp_lt_i32_e64 s[50:51], s29, v184
	v_cmp_gt_i32_e64 s[48:49], s33, v184
	v_bitop3_b32 v182, v180, s0, 16 bitop3:0xc8
	v_cmp_ne_u32_e64 s[46:47], 1, v0
	s_andn2_b64 vcc, exec, s[20:21]
	v_mov_b32_e32 v161, v93
	v_mov_b32_e32 v160, v92
	v_mov_b32_e32 v159, v91
	v_mov_b32_e32 v158, v90
	v_mov_b64_e32 v[146:147], v[118:119]
	v_mov_b64_e32 v[150:151], v[114:115]
	v_mov_b64_e32 v[154:155], v[94:95]
	s_cbranch_vccnz .LBB0_1391
	v_lshl_or_b32 v222, v182, 6, v166
	v_lshlrev_b32_e32 v222, 2, v222
	s_and_saveexec_b64 vcc, s[50:51]
	s_cbranch_execz .Lrope_skip_1
	global_load_dwordx4 v[214:217], v222, s[84:85]
	global_load_dwordx4 v[218:221], v222, s[84:85] offset:16
	global_load_dwordx4 v[242:245], v222, s[84:85] offset:128
	global_load_dwordx4 v[246:249], v222, s[84:85] offset:144
.Lrope_skip_1:
	s_or_b64 exec, exec, vcc
	v_mul_f32_e32 v0, v119, v119
	v_fmac_f32_e32 v0, v118, v118
	v_fmac_f32_e32 v0, v120, v120
	v_fmac_f32_e32 v0, v121, v121
	v_fmac_f32_e32 v0, v114, v114
	v_fmac_f32_e32 v0, v115, v115
	v_fmac_f32_e32 v0, v116, v116
	v_fmac_f32_e32 v0, v117, v117
	v_pk_mul_f32 v[148:149], v[94:95], v[94:95]
	v_pk_mul_f32 v[146:147], v[96:97], v[96:97]
	v_add_f32_e32 v0, v148, v0
	v_add_f32_e32 v0, v149, v0
	v_add_f32_e32 v0, v146, v0
	v_add_f32_e32 v0, v147, v0
	v_pk_mul_f32 v[148:149], v[90:91], v[90:91]
	v_pk_mul_f32 v[146:147], v[92:93], v[92:93]
	v_add_f32_e32 v0, v148, v0
	v_add_f32_e32 v0, v149, v0
	v_cmp_lt_i32_e32 vcc, v205, v203
	v_add_f32_e32 v0, v146, v0
	v_add_f32_e32 v0, v147, v0
	v_cndmask_b32_e32 v146, v224, v205, vcc
	v_lshlrev_b32_e32 v146, 2, v146
	ds_bpermute_b32 v146, v146, v0
	v_cmp_lt_i32_e32 vcc, v204, v203
	s_waitcnt lgkmcnt(0)
	v_add_f32_e32 v0, v0, v146
	v_cndmask_b32_e32 v146, v224, v204, vcc
	v_lshlrev_b32_e32 v146, 2, v146
	ds_bpermute_b32 v146, v146, v0
	s_waitcnt lgkmcnt(0)
	v_add_f32_e32 v0, v0, v146
	v_fmamk_f32 v0, v0, 0x3c800000, v226
	v_mul_f32_e32 v146, 0x4b800000, v0
	v_cmp_gt_f32_e32 vcc, s58, v0
	s_nop 1
	v_cndmask_b32_e32 v0, v0, v146, vcc
	v_rsq_f32_e32 v0, v0
	s_nop 0
	v_mul_f32_e32 v146, 0x45800000, v0
	v_cndmask_b32_e32 v158, v0, v146, vcc
	v_lshl_or_b32 v0, v182, 6, v166
	v_pk_mul_f32 v[146:147], v[118:119], v[158:159] op_sel_hi:[1,0]
	v_pk_mul_f32 v[148:149], v[120:121], v[158:159] op_sel_hi:[1,0]
	s_waitcnt vmcnt(0)
	v_pk_mul_f32 v[146:147], v[142:143], v[146:147]
	v_pk_mul_f32 v[148:149], v[144:145], v[148:149]
	v_lshlrev_b32_e32 v0, 2, v0
	s_and_saveexec_b64 s[20:21], s[50:51]
	s_cbranch_execz .LBB0_1383
	v_pk_mul_f32 v[156:157], v[146:147], v[214:215] op_sel:[1,1] op_sel_hi:[1,0]
	s_nop 0
	v_pk_fma_f32 v[154:155], v[146:147], v[214:215], v[156:157] op_sel_hi:[0,1,1] neg_lo:[0,0,1] neg_hi:[0,0,1]
	v_pk_fma_f32 v[146:147], v[146:147], v[214:215], v[156:157] op_sel_hi:[0,1,1]
	v_mul_f32_e32 v146, v149, v217
	v_pk_fma_f32 v[156:157], v[148:149], v[216:217], v[146:147] op_sel_hi:[1,1,0] neg_lo:[0,0,1] neg_hi:[0,0,1]
	v_mul_f32_e32 v146, v149, v216
	v_pk_fma_f32 v[148:149], v[148:149], v[216:217], v[146:147] op_sel:[0,1,0] op_sel_hi:[1,0,0]
	v_mov_b32_e32 v155, v147
	v_mov_b32_e32 v157, v148
	v_mov_b64_e32 v[146:147], v[154:155]
	v_mov_b64_e32 v[148:149], v[156:157]
.LBB0_1383:
	s_or_b64 exec, exec, s[20:21]
	v_mov_b32_e32 v159, v158
	v_mov_b32_e32 v154, v158
	v_mov_b32_e32 v155, v158
	v_pk_mul_f32 v[150:151], v[116:117], v[154:155]
	v_pk_mul_f32 v[156:157], v[114:115], v[158:159]
	v_pk_mul_f32 v[152:153], v[140:141], v[150:151]
	v_pk_mul_f32 v[150:151], v[138:139], v[156:157]
	s_and_saveexec_b64 s[20:21], s[50:51]
	s_cbranch_execz .LBB0_1385
	v_pk_mul_f32 v[156:157], v[150:151], v[218:219] op_sel:[1,1] op_sel_hi:[1,0]
	s_nop 0
	v_pk_fma_f32 v[210:211], v[150:151], v[218:219], v[156:157] op_sel_hi:[0,1,1] neg_lo:[0,0,1] neg_hi:[0,0,1]
	v_pk_fma_f32 v[150:151], v[150:151], v[218:219], v[156:157] op_sel_hi:[0,1,1]
	v_mul_f32_e32 v150, v153, v221
	v_pk_fma_f32 v[212:213], v[152:153], v[220:221], v[150:151] op_sel_hi:[1,1,0] neg_lo:[0,0,1] neg_hi:[0,0,1]
	v_mul_f32_e32 v150, v153, v220
	v_pk_fma_f32 v[152:153], v[152:153], v[220:221], v[150:151] op_sel:[0,1,0] op_sel_hi:[1,0,0]
	v_mov_b32_e32 v211, v151
	v_mov_b32_e32 v213, v152
	v_mov_b64_e32 v[150:151], v[210:211]
	v_mov_b64_e32 v[152:153], v[212:213]
.LBB0_1385:
	s_or_b64 exec, exec, s[20:21]
	v_pk_mul_f32 v[154:155], v[96:97], v[154:155]
	v_pk_mul_f32 v[160:161], v[94:95], v[158:159]
	v_pk_mul_f32 v[156:157], v[136:137], v[154:155]
	v_pk_mul_f32 v[154:155], v[134:135], v[160:161]
	s_and_saveexec_b64 s[20:21], s[50:51]
	s_cbranch_execz .LBB0_1387
	v_pk_mul_f32 v[160:161], v[154:155], v[242:243] op_sel:[1,1] op_sel_hi:[1,0]
	s_nop 0
	v_pk_fma_f32 v[210:211], v[154:155], v[242:243], v[160:161] op_sel_hi:[0,1,1] neg_lo:[0,0,1] neg_hi:[0,0,1]
	v_pk_fma_f32 v[154:155], v[154:155], v[242:243], v[160:161] op_sel_hi:[0,1,1]
	v_mul_f32_e32 v154, v157, v245
	v_pk_fma_f32 v[212:213], v[156:157], v[244:245], v[154:155] op_sel_hi:[1,1,0] neg_lo:[0,0,1] neg_hi:[0,0,1]
	v_mul_f32_e32 v154, v157, v244
	v_pk_fma_f32 v[156:157], v[156:157], v[244:245], v[154:155] op_sel:[0,1,0] op_sel_hi:[1,0,0]
	v_mov_b32_e32 v211, v155
	v_mov_b32_e32 v213, v156
	v_mov_b64_e32 v[154:155], v[210:211]
	v_mov_b64_e32 v[156:157], v[212:213]
.LBB0_1387:
	s_or_b64 exec, exec, s[20:21]
	v_mov_b32_e32 v160, v158
	v_mov_b32_e32 v161, v158
	v_pk_mul_f32 v[160:161], v[92:93], v[160:161]
	v_pk_mul_f32 v[158:159], v[90:91], v[158:159]
	v_pk_mul_f32 v[160:161], v[132:133], v[160:161]
	v_pk_mul_f32 v[158:159], v[130:131], v[158:159]
	s_and_saveexec_b64 s[20:21], s[50:51]
	s_cbranch_execz .LBB0_1389
	v_pk_mul_f32 v[196:197], v[158:159], v[246:247] op_sel:[1,1] op_sel_hi:[1,0]
	v_mul_f32_e32 v0, v161, v249
	v_pk_mul_f32 v[194:195], v[158:159], v[246:247]
	v_pk_fma_f32 v[158:159], v[158:159], v[246:247], v[196:197] op_sel_hi:[0,1,1]
	v_pk_fma_f32 v[206:207], v[160:161], v[248:249], v[0:1] op_sel_hi:[1,1,0] neg_lo:[0,0,1] neg_hi:[0,0,1]
	v_mul_f32_e32 v0, v161, v248
	v_pk_fma_f32 v[160:161], v[160:161], v[248:249], v[0:1] op_sel:[0,1,0] op_sel_hi:[1,0,0]
	v_sub_f32_e32 v158, v194, v196
	v_mov_b32_e32 v161, v160
	v_mov_b32_e32 v160, v206

.LBB0_1405:
	v_or_b32_e32 v184, 32, v180
	s_movk_i32 s0, 0x7ef
	v_mov_b64_e32 v[148:149], v[104:105]
	v_mov_b64_e32 v[152:153], v[100:101]
	v_mov_b64_e32 v[156:157], v[80:81]
	v_cmp_lt_i32_e64 s[50:51], s29, v184
	v_cmp_gt_i32_e64 s[48:49], s33, v184
	v_bitop3_b32 v182, v180, s0, 32 bitop3:0xc8
	s_and_b64 vcc, exec, s[46:47]
	v_mov_b32_e32 v161, v77
	v_mov_b32_e32 v160, v76
	v_mov_b32_e32 v159, v75
	v_mov_b32_e32 v158, v74
	v_mov_b64_e32 v[146:147], v[102:103]
	v_mov_b64_e32 v[150:151], v[98:99]
	v_mov_b64_e32 v[154:155], v[78:79]
	s_cbranch_vccnz .LBB0_1416
	v_lshl_or_b32 v222, v182, 6, v166
	v_lshlrev_b32_e32 v222, 2, v222
	s_and_saveexec_b64 vcc, s[50:51]
	s_cbranch_execz .Lrope_skip_2
	global_load_dwordx4 v[214:217], v222, s[84:85]
	global_load_dwordx4 v[218:221], v222, s[84:85] offset:16
	global_load_dwordx4 v[242:245], v222, s[84:85] offset:128
	global_load_dwordx4 v[246:249], v222, s[84:85] offset:144
.Lrope_skip_2:
	s_or_b64 exec, exec, vcc
	v_mul_f32_e32 v0, v103, v103
	v_fmac_f32_e32 v0, v102, v102
	v_fmac_f32_e32 v0, v104, v104
	v_fmac_f32_e32 v0, v105, v105
	v_fmac_f32_e32 v0, v98, v98
	v_fmac_f32_e32 v0, v99, v99
	v_fmac_f32_e32 v0, v100, v100
	v_fmac_f32_e32 v0, v101, v101
	v_pk_mul_f32 v[148:149], v[78:79], v[78:79]
	v_pk_mul_f32 v[146:147], v[80:81], v[80:81]
	v_add_f32_e32 v0, v148, v0
	v_add_f32_e32 v0, v149, v0
	v_add_f32_e32 v0, v146, v0
	v_add_f32_e32 v0, v147, v0
	v_pk_mul_f32 v[148:149], v[74:75], v[74:75]
	v_pk_mul_f32 v[146:147], v[76:77], v[76:77]
	v_add_f32_e32 v0, v148, v0
	v_add_f32_e32 v0, v149, v0
	v_cmp_lt_i32_e32 vcc, v205, v203
	v_add_f32_e32 v0, v146, v0
	v_add_f32_e32 v0, v147, v0
	v_cndmask_b32_e32 v146, v224, v205, vcc
	v_lshlrev_b32_e32 v146, 2, v146
	ds_bpermute_b32 v146, v146, v0
	v_cmp_lt_i32_e32 vcc, v204, v203
	s_waitcnt lgkmcnt(0)
	v_add_f32_e32 v0, v0, v146
	v_cndmask_b32_e32 v146, v224, v204, vcc
	v_lshlrev_b32_e32 v146, 2, v146
	ds_bpermute_b32 v146, v146, v0
	s_waitcnt lgkmcnt(0)
	v_add_f32_e32 v0, v0, v146
	v_fmamk_f32 v0, v0, 0x3c800000, v226
	v_mul_f32_e32 v146, 0x4b800000, v0
	v_cmp_gt_f32_e32 vcc, s58, v0
	s_nop 1
	v_cndmask_b32_e32 v0, v0, v146, vcc
	v_rsq_f32_e32 v0, v0
	s_nop 0
	v_mul_f32_e32 v146, 0x45800000, v0
	v_cndmask_b32_e32 v158, v0, v146, vcc
	v_lshl_or_b32 v0, v182, 6, v166
	v_pk_mul_f32 v[146:147], v[102:103], v[158:159] op_sel_hi:[1,0]
	v_pk_mul_f32 v[148:149], v[104:105], v[158:159] op_sel_hi:[1,0]
	s_waitcnt vmcnt(0)
	v_pk_mul_f32 v[146:147], v[142:143], v[146:147]
	v_pk_mul_f32 v[148:149], v[144:145], v[148:149]
	v_lshlrev_b32_e32 v0, 2, v0
	s_and_saveexec_b64 s[20:21], s[50:51]
	s_cbranch_execz .LBB0_1408
	v_pk_mul_f32 v[156:157], v[146:147], v[214:215] op_sel:[1,1] op_sel_hi:[1,0]
	s_nop 0
	v_pk_fma_f32 v[154:155], v[146:147], v[214:215], v[156:157] op_sel_hi:[0,1,1] neg_lo:[0,0,1] neg_hi:[0,0,1]
	v_pk_fma_f32 v[146:147], v[146:147], v[214:215], v[156:157] op_sel_hi:[0,1,1]
	v_mul_f32_e32 v146, v149, v217
	v_pk_fma_f32 v[156:157], v[148:149], v[216:217], v[146:147] op_sel_hi:[1,1,0] neg_lo:[0,0,1] neg_hi:[0,0,1]
	v_mul_f32_e32 v146, v149, v216
	v_pk_fma_f32 v[148:149], v[148:149], v[216:217], v[146:147] op_sel:[0,1,0] op_sel_hi:[1,0,0]
	v_mov_b32_e32 v155, v147
	v_mov_b32_e32 v157, v148
	v_mov_b64_e32 v[146:147], v[154:155]
	v_mov_b64_e32 v[148:149], v[156:157]
.LBB0_1408:
	s_or_b64 exec, exec, s[20:21]
	v_mov_b32_e32 v159, v158
	v_mov_b32_e32 v154, v158
	v_mov_b32_e32 v155, v158
	v_pk_mul_f32 v[150:151], v[100:101], v[154:155]
	v_pk_mul_f32 v[156:157], v[98:99], v[158:159]
	v_pk_mul_f32 v[152:153], v[140:141], v[150:151]
	v_pk_mul_f32 v[150:151], v[138:139], v[156:157]
	s_and_saveexec_b64 s[20:21], s[50:51]
	s_cbranch_execz .LBB0_1410
	v_pk_mul_f32 v[156:157], v[150:151], v[218:219] op_sel:[1,1] op_sel_hi:[1,0]
	s_nop 0
	v_pk_fma_f32 v[210:211], v[150:151], v[218:219], v[156:157] op_sel_hi:[0,1,1] neg_lo:[0,0,1] neg_hi:[0,0,1]
	v_pk_fma_f32 v[150:151], v[150:151], v[218:219], v[156:157] op_sel_hi:[0,1,1]
	v_mul_f32_e32 v150, v153, v221
	v_pk_fma_f32 v[212:213], v[152:153], v[220:221], v[150:151] op_sel_hi:[1,1,0] neg_lo:[0,0,1] neg_hi:[0,0,1]
	v_mul_f32_e32 v150, v153, v220
	v_pk_fma_f32 v[152:153], v[152:153], v[220:221], v[150:151] op_sel:[0,1,0] op_sel_hi:[1,0,0]
	v_mov_b32_e32 v211, v151
	v_mov_b32_e32 v213, v152
	v_mov_b64_e32 v[150:151], v[210:211]
	v_mov_b64_e32 v[152:153], v[212:213]
.LBB0_1410:
	s_or_b64 exec, exec, s[20:21]
	v_pk_mul_f32 v[154:155], v[80:81], v[154:155]
	v_pk_mul_f32 v[160:161], v[78:79], v[158:159]
	v_pk_mul_f32 v[156:157], v[136:137], v[154:155]
	v_pk_mul_f32 v[154:155], v[134:135], v[160:161]
	s_and_saveexec_b64 s[20:21], s[50:51]
	s_cbranch_execz .LBB0_1412
	v_pk_mul_f32 v[160:161], v[154:155], v[242:243] op_sel:[1,1] op_sel_hi:[1,0]
	s_nop 0
	v_pk_fma_f32 v[210:211], v[154:155], v[242:243], v[160:161] op_sel_hi:[0,1,1] neg_lo:[0,0,1] neg_hi:[0,0,1]
	v_pk_fma_f32 v[154:155], v[154:155], v[242:243], v[160:161] op_sel_hi:[0,1,1]
	v_mul_f32_e32 v154, v157, v245
	v_pk_fma_f32 v[212:213], v[156:157], v[244:245], v[154:155] op_sel_hi:[1,1,0] neg_lo:[0,0,1] neg_hi:[0,0,1]
	v_mul_f32_e32 v154, v157, v244
	v_pk_fma_f32 v[156:157], v[156:157], v[244:245], v[154:155] op_sel:[0,1,0] op_sel_hi:[1,0,0]
	v_mov_b32_e32 v211, v155
	v_mov_b32_e32 v213, v156
	v_mov_b64_e32 v[154:155], v[210:211]
	v_mov_b64_e32 v[156:157], v[212:213]
.LBB0_1412:
	s_or_b64 exec, exec, s[20:21]
	v_mov_b32_e32 v160, v158
	v_mov_b32_e32 v161, v158
	v_pk_mul_f32 v[160:161], v[76:77], v[160:161]
	v_pk_mul_f32 v[158:159], v[74:75], v[158:159]
	v_pk_mul_f32 v[160:161], v[132:133], v[160:161]
	v_pk_mul_f32 v[158:159], v[130:131], v[158:159]
	s_and_saveexec_b64 s[20:21], s[50:51]
	s_cbranch_execz .LBB0_1414
	v_pk_mul_f32 v[196:197], v[158:159], v[246:247] op_sel:[1,1] op_sel_hi:[1,0]
	v_mul_f32_e32 v0, v161, v249
	v_pk_mul_f32 v[194:195], v[158:159], v[246:247]
	v_pk_fma_f32 v[158:159], v[158:159], v[246:247], v[196:197] op_sel_hi:[0,1,1]
	v_pk_fma_f32 v[206:207], v[160:161], v[248:249], v[0:1] op_sel_hi:[1,1,0] neg_lo:[0,0,1] neg_hi:[0,0,1]
	v_mul_f32_e32 v0, v161, v248
	v_pk_fma_f32 v[160:161], v[160:161], v[248:249], v[0:1] op_sel:[0,1,0] op_sel_hi:[1,0,0]
	v_sub_f32_e32 v158, v194, v196
	v_mov_b32_e32 v161, v160
	v_mov_b32_e32 v160, v206

.LBB0_1430:
	v_or_b32_e32 v182, 48, v180
	s_movk_i32 s0, 0x7ff
	v_mov_b64_e32 v[148:149], v[88:89]
	v_mov_b64_e32 v[152:153], v[84:85]
	v_mov_b64_e32 v[156:157], v[72:73]
	v_cmp_lt_i32_e64 s[50:51], s29, v182
	v_cmp_gt_i32_e64 s[48:49], s33, v182
	v_bitop3_b32 v180, v180, s0, 48 bitop3:0xc8
	s_and_b64 vcc, exec, s[46:47]
	v_mov_b32_e32 v161, v69
	v_mov_b32_e32 v160, v68
	v_mov_b32_e32 v159, v67
	v_mov_b32_e32 v158, v66
	v_mov_b64_e32 v[146:147], v[86:87]
	v_mov_b64_e32 v[150:151], v[82:83]
	v_mov_b64_e32 v[154:155], v[70:71]
	s_cbranch_vccnz .LBB0_1441
	v_lshl_or_b32 v222, v180, 6, v166
	v_lshlrev_b32_e32 v222, 2, v222
	s_and_saveexec_b64 vcc, s[50:51]
	s_cbranch_execz .Lrope_skip_3
	global_load_dwordx4 v[214:217], v222, s[84:85]
	global_load_dwordx4 v[218:221], v222, s[84:85] offset:16
	global_load_dwordx4 v[242:245], v222, s[84:85] offset:128
	global_load_dwordx4 v[246:249], v222, s[84:85] offset:144
.Lrope_skip_3:
	s_or_b64 exec, exec, vcc
	v_mul_f32_e32 v0, v87, v87
	v_fmac_f32_e32 v0, v86, v86
	v_fmac_f32_e32 v0, v88, v88
	v_fmac_f32_e32 v0, v89, v89
	v_fmac_f32_e32 v0, v82, v82
	v_fmac_f32_e32 v0, v83, v83
	v_fmac_f32_e32 v0, v84, v84
	v_fmac_f32_e32 v0, v85, v85
	v_pk_mul_f32 v[148:149], v[70:71], v[70:71]
	v_pk_mul_f32 v[146:147], v[72:73], v[72:73]
	v_add_f32_e32 v0, v148, v0
	v_add_f32_e32 v0, v149, v0
	v_add_f32_e32 v0, v146, v0
	v_add_f32_e32 v0, v147, v0
	v_pk_mul_f32 v[148:149], v[66:67], v[66:67]
	v_pk_mul_f32 v[146:147], v[68:69], v[68:69]
	v_add_f32_e32 v0, v148, v0
	v_add_f32_e32 v0, v149, v0
	v_cmp_lt_i32_e32 vcc, v205, v203
	v_add_f32_e32 v0, v146, v0
	v_add_f32_e32 v0, v147, v0
	v_cndmask_b32_e32 v146, v224, v205, vcc
	v_lshlrev_b32_e32 v146, 2, v146
	ds_bpermute_b32 v146, v146, v0
	v_cmp_lt_i32_e32 vcc, v204, v203
	s_waitcnt lgkmcnt(0)
	v_add_f32_e32 v0, v0, v146
	v_cndmask_b32_e32 v146, v224, v204, vcc
	v_lshlrev_b32_e32 v146, 2, v146
	ds_bpermute_b32 v146, v146, v0
	s_waitcnt lgkmcnt(0)
	v_add_f32_e32 v0, v0, v146
	v_fmamk_f32 v0, v0, 0x3c800000, v226
	v_mul_f32_e32 v146, 0x4b800000, v0
	v_cmp_gt_f32_e32 vcc, s58, v0
	s_nop 1
	v_cndmask_b32_e32 v0, v0, v146, vcc
	v_rsq_f32_e32 v0, v0
	s_nop 0
	v_mul_f32_e32 v146, 0x45800000, v0
	v_cndmask_b32_e32 v158, v0, v146, vcc
	v_lshl_or_b32 v0, v180, 6, v166
	v_pk_mul_f32 v[146:147], v[86:87], v[158:159] op_sel_hi:[1,0]
	v_pk_mul_f32 v[148:149], v[88:89], v[158:159] op_sel_hi:[1,0]
	s_waitcnt vmcnt(0)
	v_pk_mul_f32 v[146:147], v[142:143], v[146:147]
	v_pk_mul_f32 v[148:149], v[144:145], v[148:149]
	v_lshlrev_b32_e32 v0, 2, v0
	s_and_saveexec_b64 s[20:21], s[50:51]
	s_cbranch_execz .LBB0_1433
	v_pk_mul_f32 v[156:157], v[146:147], v[214:215] op_sel:[1,1] op_sel_hi:[1,0]
	s_nop 0
	v_pk_fma_f32 v[154:155], v[146:147], v[214:215], v[156:157] op_sel_hi:[0,1,1] neg_lo:[0,0,1] neg_hi:[0,0,1]
	v_pk_fma_f32 v[146:147], v[146:147], v[214:215], v[156:157] op_sel_hi:[0,1,1]
	v_mul_f32_e32 v146, v149, v217
	v_pk_fma_f32 v[156:157], v[148:149], v[216:217], v[146:147] op_sel_hi:[1,1,0] neg_lo:[0,0,1] neg_hi:[0,0,1]
	v_mul_f32_e32 v146, v149, v216
	v_pk_fma_f32 v[148:149], v[148:149], v[216:217], v[146:147] op_sel:[0,1,0] op_sel_hi:[1,0,0]
	v_mov_b32_e32 v155, v147
	v_mov_b32_e32 v157, v148
	v_mov_b64_e32 v[146:147], v[154:155]
	v_mov_b64_e32 v[148:149], v[156:157]
.LBB0_1433:
	s_or_b64 exec, exec, s[20:21]
	v_mov_b32_e32 v159, v158
	v_mov_b32_e32 v154, v158
	v_mov_b32_e32 v155, v158
	v_pk_mul_f32 v[150:151], v[84:85], v[154:155]
	v_pk_mul_f32 v[156:157], v[82:83], v[158:159]
	v_pk_mul_f32 v[152:153], v[140:141], v[150:151]
	v_pk_mul_f32 v[150:151], v[138:139], v[156:157]
	s_and_saveexec_b64 s[20:21], s[50:51]
	s_cbranch_execz .LBB0_1435
	v_pk_mul_f32 v[156:157], v[150:151], v[218:219] op_sel:[1,1] op_sel_hi:[1,0]
	s_nop 0
	v_pk_fma_f32 v[210:211], v[150:151], v[218:219], v[156:157] op_sel_hi:[0,1,1] neg_lo:[0,0,1] neg_hi:[0,0,1]
	v_pk_fma_f32 v[150:151], v[150:151], v[218:219], v[156:157] op_sel_hi:[0,1,1]
	v_mul_f32_e32 v150, v153, v221
	v_pk_fma_f32 v[212:213], v[152:153], v[220:221], v[150:151] op_sel_hi:[1,1,0] neg_lo:[0,0,1] neg_hi:[0,0,1]
	v_mul_f32_e32 v150, v153, v220
	v_pk_fma_f32 v[152:153], v[152:153], v[220:221], v[150:151] op_sel:[0,1,0] op_sel_hi:[1,0,0]
	v_mov_b32_e32 v211, v151
	v_mov_b32_e32 v213, v152
	v_mov_b64_e32 v[150:151], v[210:211]
	v_mov_b64_e32 v[152:153], v[212:213]
.LBB0_1435:
	s_or_b64 exec, exec, s[20:21]
	v_pk_mul_f32 v[154:155], v[72:73], v[154:155]
	v_pk_mul_f32 v[160:161], v[70:71], v[158:159]
	v_pk_mul_f32 v[156:157], v[136:137], v[154:155]
	v_pk_mul_f32 v[154:155], v[134:135], v[160:161]
	s_and_saveexec_b64 s[20:21], s[50:51]
	s_cbranch_execz .LBB0_1437
	v_pk_mul_f32 v[160:161], v[154:155], v[242:243] op_sel:[1,1] op_sel_hi:[1,0]
	s_nop 0
	v_pk_fma_f32 v[210:211], v[154:155], v[242:243], v[160:161] op_sel_hi:[0,1,1] neg_lo:[0,0,1] neg_hi:[0,0,1]
	v_pk_fma_f32 v[154:155], v[154:155], v[242:243], v[160:161] op_sel_hi:[0,1,1]
	v_mul_f32_e32 v154, v157, v245
	v_pk_fma_f32 v[212:213], v[156:157], v[244:245], v[154:155] op_sel_hi:[1,1,0] neg_lo:[0,0,1] neg_hi:[0,0,1]
	v_mul_f32_e32 v154, v157, v244
	v_pk_fma_f32 v[156:157], v[156:157], v[244:245], v[154:155] op_sel:[0,1,0] op_sel_hi:[1,0,0]
	v_mov_b32_e32 v211, v155
	v_mov_b32_e32 v213, v156
	v_mov_b64_e32 v[154:155], v[210:211]
	v_mov_b64_e32 v[156:157], v[212:213]
.LBB0_1437:
	s_or_b64 exec, exec, s[20:21]
	v_mov_b32_e32 v160, v158
	v_mov_b32_e32 v161, v158
	v_pk_mul_f32 v[160:161], v[68:69], v[160:161]
	v_pk_mul_f32 v[158:159], v[66:67], v[158:159]
	v_pk_mul_f32 v[160:161], v[132:133], v[160:161]
	v_pk_mul_f32 v[158:159], v[130:131], v[158:159]
	s_and_saveexec_b64 s[20:21], s[50:51]
	s_cbranch_execz .LBB0_1439
	v_mul_f32_e32 v0, v161, v249
	v_pk_mul_f32 v[194:195], v[158:159], v[246:247] op_sel:[1,1] op_sel_hi:[1,0]
	v_pk_fma_f32 v[196:197], v[160:161], v[248:249], v[0:1] op_sel_hi:[1,1,0] neg_lo:[0,0,1] neg_hi:[0,0,1]
	v_mul_f32_e32 v0, v161, v248
	v_pk_mul_f32 v[184:185], v[158:159], v[246:247]
	v_pk_fma_f32 v[158:159], v[158:159], v[246:247], v[194:195] op_sel_hi:[0,1,1]
	v_pk_fma_f32 v[160:161], v[160:161], v[248:249], v[0:1] op_sel:[0,1,0] op_sel_hi:[1,0,0]
	v_sub_f32_e32 v158, v184, v194
	v_mov_b32_e32 v161, v160
	v_mov_b32_e32 v160, v196

.LBB0_1455:
	s_add_i32 s4, s26, 0x80
	v_or_b32_e32 v180, s4, v167
	v_mov_b64_e32 v[148:149], v[64:65]
	v_mov_b64_e32 v[152:153], v[60:61]
	v_mov_b64_e32 v[156:157], v[48:49]
	v_cmp_lt_i32_e64 s[50:51], s29, v180
	v_cmp_gt_i32_e64 s[48:49], s33, v180
	v_bitop3_b32 v182, s4, v231, v167 bitop3:0xc8
	s_and_b64 vcc, exec, s[46:47]
	v_mov_b32_e32 v161, v45
	v_mov_b32_e32 v160, v44
	v_mov_b32_e32 v159, v43
	v_mov_b32_e32 v158, v42
	v_mov_b64_e32 v[146:147], v[62:63]
	v_mov_b64_e32 v[150:151], v[58:59]
	v_mov_b64_e32 v[154:155], v[46:47]
	s_cbranch_vccnz .LBB0_1466
	v_lshl_or_b32 v222, v182, 6, v166
	v_lshlrev_b32_e32 v222, 2, v222
	s_and_saveexec_b64 vcc, s[50:51]
	s_cbranch_execz .Lrope_skip_4
	global_load_dwordx4 v[214:217], v222, s[84:85]
	global_load_dwordx4 v[218:221], v222, s[84:85] offset:16
	global_load_dwordx4 v[242:245], v222, s[84:85] offset:128
	global_load_dwordx4 v[246:249], v222, s[84:85] offset:144
.Lrope_skip_4:
	s_or_b64 exec, exec, vcc
	v_mul_f32_e32 v0, v63, v63
	v_fmac_f32_e32 v0, v62, v62
	v_fmac_f32_e32 v0, v64, v64
	v_fmac_f32_e32 v0, v65, v65
	v_fmac_f32_e32 v0, v58, v58
	v_fmac_f32_e32 v0, v59, v59
	v_fmac_f32_e32 v0, v60, v60
	v_fmac_f32_e32 v0, v61, v61
	v_pk_mul_f32 v[148:149], v[46:47], v[46:47]
	v_pk_mul_f32 v[146:147], v[48:49], v[48:49]
	v_add_f32_e32 v0, v148, v0
	v_add_f32_e32 v0, v149, v0
	v_add_f32_e32 v0, v146, v0
	v_add_f32_e32 v0, v147, v0
	v_pk_mul_f32 v[148:149], v[42:43], v[42:43]
	v_pk_mul_f32 v[146:147], v[44:45], v[44:45]
	v_add_f32_e32 v0, v148, v0
	v_add_f32_e32 v0, v149, v0
	v_cmp_lt_i32_e32 vcc, v205, v203
	v_add_f32_e32 v0, v146, v0
	v_add_f32_e32 v0, v147, v0
	v_cndmask_b32_e32 v146, v224, v205, vcc
	v_lshlrev_b32_e32 v146, 2, v146
	ds_bpermute_b32 v146, v146, v0
	v_cmp_lt_i32_e32 vcc, v204, v203
	s_waitcnt lgkmcnt(0)
	v_add_f32_e32 v0, v0, v146
	v_cndmask_b32_e32 v146, v224, v204, vcc
	v_lshlrev_b32_e32 v146, 2, v146
	ds_bpermute_b32 v146, v146, v0
	s_waitcnt lgkmcnt(0)
	v_add_f32_e32 v0, v0, v146
	v_fmamk_f32 v0, v0, 0x3c800000, v226
	v_mul_f32_e32 v146, 0x4b800000, v0
	v_cmp_gt_f32_e32 vcc, s58, v0
	s_nop 1
	v_cndmask_b32_e32 v0, v0, v146, vcc
	v_rsq_f32_e32 v0, v0
	s_nop 0
	v_mul_f32_e32 v146, 0x45800000, v0
	v_cndmask_b32_e32 v158, v0, v146, vcc
	v_lshl_or_b32 v0, v182, 6, v166
	v_pk_mul_f32 v[146:147], v[62:63], v[158:159] op_sel_hi:[1,0]
	v_pk_mul_f32 v[148:149], v[64:65], v[158:159] op_sel_hi:[1,0]
	s_waitcnt vmcnt(0)
	v_pk_mul_f32 v[146:147], v[142:143], v[146:147]
	v_pk_mul_f32 v[148:149], v[144:145], v[148:149]
	v_lshlrev_b32_e32 v0, 2, v0
	s_and_saveexec_b64 s[20:21], s[50:51]
	s_cbranch_execz .LBB0_1458
	v_pk_mul_f32 v[156:157], v[146:147], v[214:215] op_sel:[1,1] op_sel_hi:[1,0]
	s_nop 0
	v_pk_fma_f32 v[154:155], v[146:147], v[214:215], v[156:157] op_sel_hi:[0,1,1] neg_lo:[0,0,1] neg_hi:[0,0,1]
	v_pk_fma_f32 v[146:147], v[146:147], v[214:215], v[156:157] op_sel_hi:[0,1,1]
	v_mul_f32_e32 v146, v149, v217
	v_pk_fma_f32 v[156:157], v[148:149], v[216:217], v[146:147] op_sel_hi:[1,1,0] neg_lo:[0,0,1] neg_hi:[0,0,1]
	v_mul_f32_e32 v146, v149, v216
	v_pk_fma_f32 v[148:149], v[148:149], v[216:217], v[146:147] op_sel:[0,1,0] op_sel_hi:[1,0,0]
	v_mov_b32_e32 v155, v147
	v_mov_b32_e32 v157, v148
	v_mov_b64_e32 v[146:147], v[154:155]
	v_mov_b64_e32 v[148:149], v[156:157]
.LBB0_1458:
	s_or_b64 exec, exec, s[20:21]
	v_mov_b32_e32 v159, v158
	v_mov_b32_e32 v154, v158
	v_mov_b32_e32 v155, v158
	v_pk_mul_f32 v[150:151], v[60:61], v[154:155]
	v_pk_mul_f32 v[156:157], v[58:59], v[158:159]
	v_pk_mul_f32 v[152:153], v[140:141], v[150:151]
	v_pk_mul_f32 v[150:151], v[138:139], v[156:157]
	s_and_saveexec_b64 s[20:21], s[50:51]
	s_cbranch_execz .LBB0_1460
	v_pk_mul_f32 v[156:157], v[150:151], v[218:219] op_sel:[1,1] op_sel_hi:[1,0]
	s_nop 0
	v_pk_fma_f32 v[210:211], v[150:151], v[218:219], v[156:157] op_sel_hi:[0,1,1] neg_lo:[0,0,1] neg_hi:[0,0,1]
	v_pk_fma_f32 v[150:151], v[150:151], v[218:219], v[156:157] op_sel_hi:[0,1,1]
	v_mul_f32_e32 v150, v153, v221
	v_pk_fma_f32 v[212:213], v[152:153], v[220:221], v[150:151] op_sel_hi:[1,1,0] neg_lo:[0,0,1] neg_hi:[0,0,1]
	v_mul_f32_e32 v150, v153, v220
	v_pk_fma_f32 v[152:153], v[152:153], v[220:221], v[150:151] op_sel:[0,1,0] op_sel_hi:[1,0,0]
	v_mov_b32_e32 v211, v151
	v_mov_b32_e32 v213, v152
	v_mov_b64_e32 v[150:151], v[210:211]
	v_mov_b64_e32 v[152:153], v[212:213]
.LBB0_1460:
	s_or_b64 exec, exec, s[20:21]
	v_pk_mul_f32 v[154:155], v[48:49], v[154:155]
	v_pk_mul_f32 v[160:161], v[46:47], v[158:159]
	v_pk_mul_f32 v[156:157], v[136:137], v[154:155]
	v_pk_mul_f32 v[154:155], v[134:135], v[160:161]
	s_and_saveexec_b64 s[20:21], s[50:51]
	s_cbranch_execz .LBB0_1462
	v_pk_mul_f32 v[160:161], v[154:155], v[242:243] op_sel:[1,1] op_sel_hi:[1,0]
	s_nop 0
	v_pk_fma_f32 v[210:211], v[154:155], v[242:243], v[160:161] op_sel_hi:[0,1,1] neg_lo:[0,0,1] neg_hi:[0,0,1]
	v_pk_fma_f32 v[154:155], v[154:155], v[242:243], v[160:161] op_sel_hi:[0,1,1]
	v_mul_f32_e32 v154, v157, v245
	v_pk_fma_f32 v[212:213], v[156:157], v[244:245], v[154:155] op_sel_hi:[1,1,0] neg_lo:[0,0,1] neg_hi:[0,0,1]
	v_mul_f32_e32 v154, v157, v244
	v_pk_fma_f32 v[156:157], v[156:157], v[244:245], v[154:155] op_sel:[0,1,0] op_sel_hi:[1,0,0]
	v_mov_b32_e32 v211, v155
	v_mov_b32_e32 v213, v156
	v_mov_b64_e32 v[154:155], v[210:211]
	v_mov_b64_e32 v[156:157], v[212:213]
.LBB0_1462:
	s_or_b64 exec, exec, s[20:21]
	v_mov_b32_e32 v160, v158
	v_mov_b32_e32 v161, v158
	v_pk_mul_f32 v[160:161], v[44:45], v[160:161]
	v_pk_mul_f32 v[158:159], v[42:43], v[158:159]
	v_pk_mul_f32 v[160:161], v[132:133], v[160:161]
	v_pk_mul_f32 v[158:159], v[130:131], v[158:159]
	s_and_saveexec_b64 s[20:21], s[50:51]
	s_cbranch_execz .LBB0_1464
	v_mul_f32_e32 v0, v161, v249
	v_pk_mul_f32 v[194:195], v[158:159], v[246:247] op_sel:[1,1] op_sel_hi:[1,0]
	v_pk_fma_f32 v[196:197], v[160:161], v[248:249], v[0:1] op_sel_hi:[1,1,0] neg_lo:[0,0,1] neg_hi:[0,0,1]
	v_mul_f32_e32 v0, v161, v248
	v_pk_mul_f32 v[184:185], v[158:159], v[246:247]
	v_pk_fma_f32 v[158:159], v[158:159], v[246:247], v[194:195] op_sel_hi:[0,1,1]
	v_pk_fma_f32 v[160:161], v[160:161], v[248:249], v[0:1] op_sel:[0,1,0] op_sel_hi:[1,0,0]
	v_sub_f32_e32 v158, v184, v194
	v_mov_b32_e32 v161, v160
	v_mov_b32_e32 v160, v196

.LBB0_1480:
	v_or_b32_e32 v184, 16, v180
	s_movk_i32 s0, 0x7df
	v_mov_b64_e32 v[148:149], v[56:57]
	v_mov_b64_e32 v[152:153], v[52:53]
	v_mov_b64_e32 v[156:157], v[32:33]
	v_cmp_lt_i32_e64 s[50:51], s29, v184
	v_cmp_gt_i32_e64 s[48:49], s33, v184
	v_bitop3_b32 v182, v180, s0, 16 bitop3:0xc8
	s_and_b64 vcc, exec, s[46:47]
	v_mov_b32_e32 v161, v29
	v_mov_b32_e32 v160, v28
	v_mov_b32_e32 v159, v27
	v_mov_b32_e32 v158, v26
	v_mov_b64_e32 v[146:147], v[54:55]
	v_mov_b64_e32 v[150:151], v[50:51]
	v_mov_b64_e32 v[154:155], v[30:31]
	s_cbranch_vccnz .LBB0_1491
	v_lshl_or_b32 v222, v182, 6, v166
	v_lshlrev_b32_e32 v222, 2, v222
	s_and_saveexec_b64 vcc, s[50:51]
	s_cbranch_execz .Lrope_skip_5
	global_load_dwordx4 v[214:217], v222, s[84:85]
	global_load_dwordx4 v[218:221], v222, s[84:85] offset:16
	global_load_dwordx4 v[242:245], v222, s[84:85] offset:128
	global_load_dwordx4 v[246:249], v222, s[84:85] offset:144
.Lrope_skip_5:
	s_or_b64 exec, exec, vcc
	v_mul_f32_e32 v0, v55, v55
	v_fmac_f32_e32 v0, v54, v54
	v_fmac_f32_e32 v0, v56, v56
	v_fmac_f32_e32 v0, v57, v57
	v_fmac_f32_e32 v0, v50, v50
	v_fmac_f32_e32 v0, v51, v51
	v_fmac_f32_e32 v0, v52, v52
	v_fmac_f32_e32 v0, v53, v53
	v_pk_mul_f32 v[148:149], v[30:31], v[30:31]
	v_pk_mul_f32 v[146:147], v[32:33], v[32:33]
	v_add_f32_e32 v0, v148, v0
	v_add_f32_e32 v0, v149, v0
	v_add_f32_e32 v0, v146, v0
	v_add_f32_e32 v0, v147, v0
	v_pk_mul_f32 v[148:149], v[26:27], v[26:27]
	v_pk_mul_f32 v[146:147], v[28:29], v[28:29]
	v_add_f32_e32 v0, v148, v0
	v_add_f32_e32 v0, v149, v0
	v_cmp_lt_i32_e32 vcc, v205, v203
	v_add_f32_e32 v0, v146, v0
	v_add_f32_e32 v0, v147, v0
	v_cndmask_b32_e32 v146, v224, v205, vcc
	v_lshlrev_b32_e32 v146, 2, v146
	ds_bpermute_b32 v146, v146, v0
	v_cmp_lt_i32_e32 vcc, v204, v203
	s_waitcnt lgkmcnt(0)
	v_add_f32_e32 v0, v0, v146
	v_cndmask_b32_e32 v146, v224, v204, vcc
	v_lshlrev_b32_e32 v146, 2, v146
	ds_bpermute_b32 v146, v146, v0
	s_waitcnt lgkmcnt(0)
	v_add_f32_e32 v0, v0, v146
	v_fmamk_f32 v0, v0, 0x3c800000, v226
	v_mul_f32_e32 v146, 0x4b800000, v0
	v_cmp_gt_f32_e32 vcc, s58, v0
	s_nop 1
	v_cndmask_b32_e32 v0, v0, v146, vcc
	v_rsq_f32_e32 v0, v0
	s_nop 0
	v_mul_f32_e32 v146, 0x45800000, v0
	v_cndmask_b32_e32 v158, v0, v146, vcc
	v_lshl_or_b32 v0, v182, 6, v166
	v_pk_mul_f32 v[146:147], v[54:55], v[158:159] op_sel_hi:[1,0]
	v_pk_mul_f32 v[148:149], v[56:57], v[158:159] op_sel_hi:[1,0]
	s_waitcnt vmcnt(0)
	v_pk_mul_f32 v[146:147], v[142:143], v[146:147]
	v_pk_mul_f32 v[148:149], v[144:145], v[148:149]
	v_lshlrev_b32_e32 v0, 2, v0
	s_and_saveexec_b64 s[20:21], s[50:51]
	s_cbranch_execz .LBB0_1483
	v_pk_mul_f32 v[156:157], v[146:147], v[214:215] op_sel:[1,1] op_sel_hi:[1,0]
	s_nop 0
	v_pk_fma_f32 v[154:155], v[146:147], v[214:215], v[156:157] op_sel_hi:[0,1,1] neg_lo:[0,0,1] neg_hi:[0,0,1]
	v_pk_fma_f32 v[146:147], v[146:147], v[214:215], v[156:157] op_sel_hi:[0,1,1]
	v_mul_f32_e32 v146, v149, v217
	v_pk_fma_f32 v[156:157], v[148:149], v[216:217], v[146:147] op_sel_hi:[1,1,0] neg_lo:[0,0,1] neg_hi:[0,0,1]
	v_mul_f32_e32 v146, v149, v216
	v_pk_fma_f32 v[148:149], v[148:149], v[216:217], v[146:147] op_sel:[0,1,0] op_sel_hi:[1,0,0]
	v_mov_b32_e32 v155, v147
	v_mov_b32_e32 v157, v148
	v_mov_b64_e32 v[146:147], v[154:155]
	v_mov_b64_e32 v[148:149], v[156:157]
.LBB0_1483:
	s_or_b64 exec, exec, s[20:21]
	v_mov_b32_e32 v159, v158
	v_mov_b32_e32 v154, v158
	v_mov_b32_e32 v155, v158
	v_pk_mul_f32 v[150:151], v[52:53], v[154:155]
	v_pk_mul_f32 v[156:157], v[50:51], v[158:159]
	v_pk_mul_f32 v[152:153], v[140:141], v[150:151]
	v_pk_mul_f32 v[150:151], v[138:139], v[156:157]
	s_and_saveexec_b64 s[20:21], s[50:51]
	s_cbranch_execz .LBB0_1485
	v_pk_mul_f32 v[156:157], v[150:151], v[218:219] op_sel:[1,1] op_sel_hi:[1,0]
	s_nop 0
	v_pk_fma_f32 v[210:211], v[150:151], v[218:219], v[156:157] op_sel_hi:[0,1,1] neg_lo:[0,0,1] neg_hi:[0,0,1]
	v_pk_fma_f32 v[150:151], v[150:151], v[218:219], v[156:157] op_sel_hi:[0,1,1]
	v_mul_f32_e32 v150, v153, v221
	v_pk_fma_f32 v[212:213], v[152:153], v[220:221], v[150:151] op_sel_hi:[1,1,0] neg_lo:[0,0,1] neg_hi:[0,0,1]
	v_mul_f32_e32 v150, v153, v220
	v_pk_fma_f32 v[152:153], v[152:153], v[220:221], v[150:151] op_sel:[0,1,0] op_sel_hi:[1,0,0]
	v_mov_b32_e32 v211, v151
	v_mov_b32_e32 v213, v152
	v_mov_b64_e32 v[150:151], v[210:211]
	v_mov_b64_e32 v[152:153], v[212:213]
.LBB0_1485:
	s_or_b64 exec, exec, s[20:21]
	v_pk_mul_f32 v[154:155], v[32:33], v[154:155]
	v_pk_mul_f32 v[160:161], v[30:31], v[158:159]
	v_pk_mul_f32 v[156:157], v[136:137], v[154:155]
	v_pk_mul_f32 v[154:155], v[134:135], v[160:161]
	s_and_saveexec_b64 s[20:21], s[50:51]
	s_cbranch_execz .LBB0_1487
	v_pk_mul_f32 v[160:161], v[154:155], v[242:243] op_sel:[1,1] op_sel_hi:[1,0]
	s_nop 0
	v_pk_fma_f32 v[210:211], v[154:155], v[242:243], v[160:161] op_sel_hi:[0,1,1] neg_lo:[0,0,1] neg_hi:[0,0,1]
	v_pk_fma_f32 v[154:155], v[154:155], v[242:243], v[160:161] op_sel_hi:[0,1,1]
	v_mul_f32_e32 v154, v157, v245
	v_pk_fma_f32 v[212:213], v[156:157], v[244:245], v[154:155] op_sel_hi:[1,1,0] neg_lo:[0,0,1] neg_hi:[0,0,1]
	v_mul_f32_e32 v154, v157, v244
	v_pk_fma_f32 v[156:157], v[156:157], v[244:245], v[154:155] op_sel:[0,1,0] op_sel_hi:[1,0,0]
	v_mov_b32_e32 v211, v155
	v_mov_b32_e32 v213, v156
	v_mov_b64_e32 v[154:155], v[210:211]
	v_mov_b64_e32 v[156:157], v[212:213]
.LBB0_1487:
	s_or_b64 exec, exec, s[20:21]
	v_mov_b32_e32 v160, v158
	v_mov_b32_e32 v161, v158
	v_pk_mul_f32 v[160:161], v[28:29], v[160:161]
	v_pk_mul_f32 v[158:159], v[26:27], v[158:159]
	v_pk_mul_f32 v[160:161], v[132:133], v[160:161]
	v_pk_mul_f32 v[158:159], v[130:131], v[158:159]
	s_and_saveexec_b64 s[20:21], s[50:51]
	s_cbranch_execz .LBB0_1489
	v_pk_mul_f32 v[196:197], v[158:159], v[246:247] op_sel:[1,1] op_sel_hi:[1,0]
	v_mul_f32_e32 v0, v161, v249
	v_pk_mul_f32 v[194:195], v[158:159], v[246:247]
	v_pk_fma_f32 v[158:159], v[158:159], v[246:247], v[196:197] op_sel_hi:[0,1,1]
	v_pk_fma_f32 v[206:207], v[160:161], v[248:249], v[0:1] op_sel_hi:[1,1,0] neg_lo:[0,0,1] neg_hi:[0,0,1]
	v_mul_f32_e32 v0, v161, v248
	v_pk_fma_f32 v[160:161], v[160:161], v[248:249], v[0:1] op_sel:[0,1,0] op_sel_hi:[1,0,0]
	v_sub_f32_e32 v158, v194, v196
	v_mov_b32_e32 v161, v160
	v_mov_b32_e32 v160, v206

.LBB0_1505:
	v_or_b32_e32 v184, 32, v180
	s_movk_i32 s0, 0x7ef
	v_mov_b64_e32 v[148:149], v[40:41]
	v_mov_b64_e32 v[152:153], v[36:37]
	v_mov_b64_e32 v[156:157], v[20:21]
	v_cmp_lt_i32_e64 s[50:51], s29, v184
	v_cmp_gt_i32_e64 s[48:49], s33, v184
	v_bitop3_b32 v182, v180, s0, 32 bitop3:0xc8
	s_and_b64 vcc, exec, s[46:47]
	v_mov_b32_e32 v161, v13
	v_mov_b32_e32 v160, v12
	v_mov_b32_e32 v159, v11
	v_mov_b32_e32 v158, v10
	v_mov_b64_e32 v[146:147], v[38:39]
	v_mov_b64_e32 v[150:151], v[34:35]
	v_mov_b64_e32 v[154:155], v[18:19]
	s_cbranch_vccnz .LBB0_1516
	v_lshl_or_b32 v222, v182, 6, v166
	v_lshlrev_b32_e32 v222, 2, v222
	s_and_saveexec_b64 vcc, s[50:51]
	s_cbranch_execz .Lrope_skip_6
	global_load_dwordx4 v[214:217], v222, s[84:85]
	global_load_dwordx4 v[218:221], v222, s[84:85] offset:16
	global_load_dwordx4 v[242:245], v222, s[84:85] offset:128
	global_load_dwordx4 v[246:249], v222, s[84:85] offset:144
.Lrope_skip_6:
	s_or_b64 exec, exec, vcc
	v_mul_f32_e32 v0, v39, v39
	v_fmac_f32_e32 v0, v38, v38
	v_fmac_f32_e32 v0, v40, v40
	v_fmac_f32_e32 v0, v41, v41
	v_fmac_f32_e32 v0, v34, v34
	v_fmac_f32_e32 v0, v35, v35
	v_fmac_f32_e32 v0, v36, v36
	v_fmac_f32_e32 v0, v37, v37
	v_pk_mul_f32 v[148:149], v[18:19], v[18:19]
	v_pk_mul_f32 v[146:147], v[20:21], v[20:21]
	v_add_f32_e32 v0, v148, v0
	v_add_f32_e32 v0, v149, v0
	v_add_f32_e32 v0, v146, v0
	v_add_f32_e32 v0, v147, v0
	v_pk_mul_f32 v[148:149], v[10:11], v[10:11]
	v_pk_mul_f32 v[146:147], v[12:13], v[12:13]
	v_add_f32_e32 v0, v148, v0
	v_add_f32_e32 v0, v149, v0
	v_cmp_lt_i32_e32 vcc, v205, v203
	v_add_f32_e32 v0, v146, v0
	v_add_f32_e32 v0, v147, v0
	v_cndmask_b32_e32 v146, v224, v205, vcc
	v_lshlrev_b32_e32 v146, 2, v146
	ds_bpermute_b32 v146, v146, v0
	v_cmp_lt_i32_e32 vcc, v204, v203
	s_waitcnt lgkmcnt(0)
	v_add_f32_e32 v0, v0, v146
	v_cndmask_b32_e32 v146, v224, v204, vcc
	v_lshlrev_b32_e32 v146, 2, v146
	ds_bpermute_b32 v146, v146, v0
	s_waitcnt lgkmcnt(0)
	v_add_f32_e32 v0, v0, v146
	v_fmamk_f32 v0, v0, 0x3c800000, v226
	v_mul_f32_e32 v146, 0x4b800000, v0
	v_cmp_gt_f32_e32 vcc, s58, v0
	s_nop 1
	v_cndmask_b32_e32 v0, v0, v146, vcc
	v_rsq_f32_e32 v0, v0
	s_nop 0
	v_mul_f32_e32 v146, 0x45800000, v0
	v_cndmask_b32_e32 v158, v0, v146, vcc
	v_lshl_or_b32 v0, v182, 6, v166
	v_pk_mul_f32 v[146:147], v[38:39], v[158:159] op_sel_hi:[1,0]
	v_pk_mul_f32 v[148:149], v[40:41], v[158:159] op_sel_hi:[1,0]
	s_waitcnt vmcnt(0)
	v_pk_mul_f32 v[146:147], v[142:143], v[146:147]
	v_pk_mul_f32 v[148:149], v[144:145], v[148:149]
	v_lshlrev_b32_e32 v0, 2, v0
	s_and_saveexec_b64 s[20:21], s[50:51]
	s_cbranch_execz .LBB0_1508
	v_pk_mul_f32 v[156:157], v[146:147], v[214:215] op_sel:[1,1] op_sel_hi:[1,0]
	s_nop 0
	v_pk_fma_f32 v[154:155], v[146:147], v[214:215], v[156:157] op_sel_hi:[0,1,1] neg_lo:[0,0,1] neg_hi:[0,0,1]
	v_pk_fma_f32 v[146:147], v[146:147], v[214:215], v[156:157] op_sel_hi:[0,1,1]
	v_mul_f32_e32 v146, v149, v217
	v_pk_fma_f32 v[156:157], v[148:149], v[216:217], v[146:147] op_sel_hi:[1,1,0] neg_lo:[0,0,1] neg_hi:[0,0,1]
	v_mul_f32_e32 v146, v149, v216
	v_pk_fma_f32 v[148:149], v[148:149], v[216:217], v[146:147] op_sel:[0,1,0] op_sel_hi:[1,0,0]
	v_mov_b32_e32 v155, v147
	v_mov_b32_e32 v157, v148
	v_mov_b64_e32 v[146:147], v[154:155]
	v_mov_b64_e32 v[148:149], v[156:157]
.LBB0_1508:
	s_or_b64 exec, exec, s[20:21]
	v_mov_b32_e32 v159, v158
	v_mov_b32_e32 v154, v158
	v_mov_b32_e32 v155, v158
	v_pk_mul_f32 v[150:151], v[36:37], v[154:155]
	v_pk_mul_f32 v[156:157], v[34:35], v[158:159]
	v_pk_mul_f32 v[152:153], v[140:141], v[150:151]
	v_pk_mul_f32 v[150:151], v[138:139], v[156:157]
	s_and_saveexec_b64 s[20:21], s[50:51]
	s_cbranch_execz .LBB0_1510
	v_pk_mul_f32 v[156:157], v[150:151], v[218:219] op_sel:[1,1] op_sel_hi:[1,0]
	s_nop 0
	v_pk_fma_f32 v[210:211], v[150:151], v[218:219], v[156:157] op_sel_hi:[0,1,1] neg_lo:[0,0,1] neg_hi:[0,0,1]
	v_pk_fma_f32 v[150:151], v[150:151], v[218:219], v[156:157] op_sel_hi:[0,1,1]
	v_mul_f32_e32 v150, v153, v221
	v_pk_fma_f32 v[212:213], v[152:153], v[220:221], v[150:151] op_sel_hi:[1,1,0] neg_lo:[0,0,1] neg_hi:[0,0,1]
	v_mul_f32_e32 v150, v153, v220
	v_pk_fma_f32 v[152:153], v[152:153], v[220:221], v[150:151] op_sel:[0,1,0] op_sel_hi:[1,0,0]
	v_mov_b32_e32 v211, v151
	v_mov_b32_e32 v213, v152
	v_mov_b64_e32 v[150:151], v[210:211]
	v_mov_b64_e32 v[152:153], v[212:213]
.LBB0_1510:
	s_or_b64 exec, exec, s[20:21]
	v_pk_mul_f32 v[154:155], v[20:21], v[154:155]
	v_pk_mul_f32 v[160:161], v[18:19], v[158:159]
	v_pk_mul_f32 v[156:157], v[136:137], v[154:155]
	v_pk_mul_f32 v[154:155], v[134:135], v[160:161]
	s_and_saveexec_b64 s[20:21], s[50:51]
	s_cbranch_execz .LBB0_1512
	v_pk_mul_f32 v[160:161], v[154:155], v[242:243] op_sel:[1,1] op_sel_hi:[1,0]
	s_nop 0
	v_pk_fma_f32 v[210:211], v[154:155], v[242:243], v[160:161] op_sel_hi:[0,1,1] neg_lo:[0,0,1] neg_hi:[0,0,1]
	v_pk_fma_f32 v[154:155], v[154:155], v[242:243], v[160:161] op_sel_hi:[0,1,1]
	v_mul_f32_e32 v154, v157, v245
	v_pk_fma_f32 v[212:213], v[156:157], v[244:245], v[154:155] op_sel_hi:[1,1,0] neg_lo:[0,0,1] neg_hi:[0,0,1]
	v_mul_f32_e32 v154, v157, v244
	v_pk_fma_f32 v[156:157], v[156:157], v[244:245], v[154:155] op_sel:[0,1,0] op_sel_hi:[1,0,0]
	v_mov_b32_e32 v211, v155
	v_mov_b32_e32 v213, v156
	v_mov_b64_e32 v[154:155], v[210:211]
	v_mov_b64_e32 v[156:157], v[212:213]
.LBB0_1512:
	s_or_b64 exec, exec, s[20:21]
	v_mov_b32_e32 v160, v158
	v_mov_b32_e32 v161, v158
	v_pk_mul_f32 v[160:161], v[12:13], v[160:161]
	v_pk_mul_f32 v[158:159], v[10:11], v[158:159]
	v_pk_mul_f32 v[160:161], v[132:133], v[160:161]
	v_pk_mul_f32 v[158:159], v[130:131], v[158:159]
	s_and_saveexec_b64 s[20:21], s[50:51]
	s_cbranch_execz .LBB0_1514
	v_pk_mul_f32 v[196:197], v[158:159], v[246:247] op_sel:[1,1] op_sel_hi:[1,0]
	v_mul_f32_e32 v0, v161, v249
	v_pk_mul_f32 v[194:195], v[158:159], v[246:247]
	v_pk_fma_f32 v[158:159], v[158:159], v[246:247], v[196:197] op_sel_hi:[0,1,1]
	v_pk_fma_f32 v[206:207], v[160:161], v[248:249], v[0:1] op_sel_hi:[1,1,0] neg_lo:[0,0,1] neg_hi:[0,0,1]
	v_mul_f32_e32 v0, v161, v248
	v_pk_fma_f32 v[160:161], v[160:161], v[248:249], v[0:1] op_sel:[0,1,0] op_sel_hi:[1,0,0]
	v_sub_f32_e32 v158, v194, v196
	v_mov_b32_e32 v161, v160
	v_mov_b32_e32 v160, v206

.LBB0_1530:
	v_or_b32_e32 v182, 48, v180
	s_movk_i32 s0, 0x7ff
	v_mov_b64_e32 v[148:149], v[24:25]
	v_mov_b64_e32 v[152:153], v[16:17]
	v_mov_b64_e32 v[156:157], v[8:9]
	v_cmp_lt_i32_e64 s[50:51], s29, v182
	v_cmp_gt_i32_e64 s[48:49], s33, v182
	v_bitop3_b32 v180, v180, s0, 48 bitop3:0xc8
	s_and_b64 vcc, exec, s[46:47]
	v_mov_b32_e32 v161, v5
	v_mov_b32_e32 v160, v4
	v_mov_b32_e32 v159, v3
	v_mov_b32_e32 v158, v2
	v_mov_b64_e32 v[146:147], v[22:23]
	v_mov_b64_e32 v[150:151], v[14:15]
	v_mov_b64_e32 v[154:155], v[6:7]
	s_cbranch_vccnz .LBB0_1541
	v_lshl_or_b32 v222, v180, 6, v166
	v_lshlrev_b32_e32 v222, 2, v222
	s_and_saveexec_b64 vcc, s[50:51]
	s_cbranch_execz .Lrope_skip_7
	global_load_dwordx4 v[214:217], v222, s[84:85]
	global_load_dwordx4 v[218:221], v222, s[84:85] offset:16
	global_load_dwordx4 v[242:245], v222, s[84:85] offset:128
	global_load_dwordx4 v[246:249], v222, s[84:85] offset:144
.Lrope_skip_7:
	s_or_b64 exec, exec, vcc
	v_mul_f32_e32 v0, v23, v23
	v_fmac_f32_e32 v0, v22, v22
	v_fmac_f32_e32 v0, v24, v24
	v_fmac_f32_e32 v0, v25, v25
	v_fmac_f32_e32 v0, v14, v14
	v_fmac_f32_e32 v0, v15, v15
	v_fmac_f32_e32 v0, v16, v16
	v_fmac_f32_e32 v0, v17, v17
	v_pk_mul_f32 v[148:149], v[6:7], v[6:7]
	v_pk_mul_f32 v[146:147], v[8:9], v[8:9]
	v_add_f32_e32 v0, v148, v0
	v_add_f32_e32 v0, v149, v0
	v_add_f32_e32 v0, v146, v0
	v_add_f32_e32 v0, v147, v0
	v_pk_mul_f32 v[148:149], v[2:3], v[2:3]
	v_pk_mul_f32 v[146:147], v[4:5], v[4:5]
	v_add_f32_e32 v0, v148, v0
	v_add_f32_e32 v0, v149, v0
	v_cmp_lt_i32_e32 vcc, v205, v203
	v_add_f32_e32 v0, v146, v0
	v_add_f32_e32 v0, v147, v0
	v_cndmask_b32_e32 v146, v224, v205, vcc
	v_lshlrev_b32_e32 v146, 2, v146
	ds_bpermute_b32 v146, v146, v0
	v_cmp_lt_i32_e32 vcc, v204, v203
	s_waitcnt lgkmcnt(0)
	v_add_f32_e32 v0, v0, v146
	v_cndmask_b32_e32 v146, v224, v204, vcc
	v_lshlrev_b32_e32 v146, 2, v146
	ds_bpermute_b32 v146, v146, v0
	s_waitcnt lgkmcnt(0)
	v_add_f32_e32 v0, v0, v146
	v_fmamk_f32 v0, v0, 0x3c800000, v226
	v_mul_f32_e32 v146, 0x4b800000, v0
	v_cmp_gt_f32_e32 vcc, s58, v0
	s_nop 1
	v_cndmask_b32_e32 v0, v0, v146, vcc
	v_rsq_f32_e32 v0, v0
	s_nop 0
	v_mul_f32_e32 v146, 0x45800000, v0
	v_cndmask_b32_e32 v158, v0, v146, vcc
	v_lshl_or_b32 v0, v180, 6, v166
	v_pk_mul_f32 v[146:147], v[22:23], v[158:159] op_sel_hi:[1,0]
	v_pk_mul_f32 v[148:149], v[24:25], v[158:159] op_sel_hi:[1,0]
	s_waitcnt vmcnt(0)
	v_pk_mul_f32 v[146:147], v[142:143], v[146:147]
	v_pk_mul_f32 v[148:149], v[144:145], v[148:149]
	v_lshlrev_b32_e32 v0, 2, v0
	s_and_saveexec_b64 s[20:21], s[50:51]
	s_cbranch_execz .LBB0_1533
	v_pk_mul_f32 v[152:153], v[146:147], v[214:215] op_sel:[1,1] op_sel_hi:[1,0]
	s_nop 0
	v_pk_fma_f32 v[150:151], v[146:147], v[214:215], v[152:153] op_sel_hi:[0,1,1] neg_lo:[0,0,1] neg_hi:[0,0,1]
	v_pk_fma_f32 v[142:143], v[146:147], v[214:215], v[152:153] op_sel_hi:[0,1,1]
	v_mul_f32_e32 v142, v149, v217
	v_pk_fma_f32 v[152:153], v[148:149], v[216:217], v[142:143] op_sel_hi:[1,1,0] neg_lo:[0,0,1] neg_hi:[0,0,1]
	v_mul_f32_e32 v142, v149, v216
	v_pk_fma_f32 v[144:145], v[148:149], v[216:217], v[142:143] op_sel:[0,1,0] op_sel_hi:[1,0,0]
	v_mov_b32_e32 v151, v143
	v_mov_b32_e32 v153, v144
	v_mov_b64_e32 v[146:147], v[150:151]
	v_mov_b64_e32 v[148:149], v[152:153]
.LBB0_1533:
	s_or_b64 exec, exec, s[20:21]
	v_mov_b32_e32 v159, v158
	v_mov_b32_e32 v142, v158
	v_mov_b32_e32 v143, v158
	v_pk_mul_f32 v[144:145], v[16:17], v[142:143]
	v_pk_mul_f32 v[150:151], v[14:15], v[158:159]
	v_pk_mul_f32 v[152:153], v[140:141], v[144:145]
	v_pk_mul_f32 v[150:151], v[138:139], v[150:151]
	s_and_saveexec_b64 s[20:21], s[50:51]
	s_cbranch_execz .LBB0_1535
	v_pk_mul_f32 v[144:145], v[150:151], v[218:219] op_sel:[1,1] op_sel_hi:[1,0]
	s_nop 0
	v_pk_fma_f32 v[154:155], v[150:151], v[218:219], v[144:145] op_sel_hi:[0,1,1] neg_lo:[0,0,1] neg_hi:[0,0,1]
	v_pk_fma_f32 v[138:139], v[150:151], v[218:219], v[144:145] op_sel_hi:[0,1,1]
	v_mul_f32_e32 v138, v153, v221
	v_pk_fma_f32 v[156:157], v[152:153], v[220:221], v[138:139] op_sel_hi:[1,1,0] neg_lo:[0,0,1] neg_hi:[0,0,1]
	v_mul_f32_e32 v138, v153, v220
	v_pk_fma_f32 v[140:141], v[152:153], v[220:221], v[138:139] op_sel:[0,1,0] op_sel_hi:[1,0,0]
	v_mov_b32_e32 v155, v139
	v_mov_b32_e32 v157, v140
	v_mov_b64_e32 v[150:151], v[154:155]
	v_mov_b64_e32 v[152:153], v[156:157]
.LBB0_1535:
	s_or_b64 exec, exec, s[20:21]
	v_pk_mul_f32 v[138:139], v[8:9], v[142:143]
	v_pk_mul_f32 v[140:141], v[6:7], v[158:159]
	v_pk_mul_f32 v[156:157], v[136:137], v[138:139]
	v_pk_mul_f32 v[154:155], v[134:135], v[140:141]
	s_and_saveexec_b64 s[20:21], s[50:51]
	s_cbranch_execz .LBB0_1537
	v_pk_mul_f32 v[140:141], v[154:155], v[242:243] op_sel:[1,1] op_sel_hi:[1,0]
	s_nop 0
	v_pk_fma_f32 v[138:139], v[154:155], v[242:243], v[140:141] op_sel_hi:[0,1,1] neg_lo:[0,0,1] neg_hi:[0,0,1]
	v_pk_fma_f32 v[134:135], v[154:155], v[242:243], v[140:141] op_sel_hi:[0,1,1]
	v_mul_f32_e32 v134, v157, v245
	v_pk_fma_f32 v[140:141], v[156:157], v[244:245], v[134:135] op_sel_hi:[1,1,0] neg_lo:[0,0,1] neg_hi:[0,0,1]
	v_mul_f32_e32 v134, v157, v244
	v_pk_fma_f32 v[136:137], v[156:157], v[244:245], v[134:135] op_sel:[0,1,0] op_sel_hi:[1,0,0]
	v_mov_b32_e32 v139, v135
	v_mov_b32_e32 v141, v136
	v_mov_b64_e32 v[156:157], v[140:141]
	v_mov_b64_e32 v[154:155], v[138:139]
.LBB0_1537:
	s_or_b64 exec, exec, s[20:21]
	v_mov_b32_e32 v134, v158
	v_mov_b32_e32 v135, v158
	v_pk_mul_f32 v[134:135], v[4:5], v[134:135]
	v_pk_mul_f32 v[136:137], v[2:3], v[158:159]
	v_pk_mul_f32 v[160:161], v[132:133], v[134:135]
	v_pk_mul_f32 v[158:159], v[130:131], v[136:137]
	s_and_saveexec_b64 s[20:21], s[50:51]
	s_cbranch_execz .LBB0_1539
	v_pk_mul_f32 v[136:137], v[158:159], v[246:247] op_sel:[1,1] op_sel_hi:[1,0]
	v_mul_f32_e32 v0, v161, v249
	v_pk_mul_f32 v[134:135], v[158:159], v[246:247]
	v_pk_fma_f32 v[158:159], v[158:159], v[246:247], v[136:137] op_sel_hi:[0,1,1]
	v_pk_fma_f32 v[130:131], v[160:161], v[248:249], v[0:1] op_sel_hi:[1,1,0] neg_lo:[0,0,1] neg_hi:[0,0,1]
	v_mul_f32_e32 v0, v161, v248
	v_pk_fma_f32 v[132:133], v[160:161], v[248:249], v[0:1] op_sel:[0,1,0] op_sel_hi:[1,0,0]
	v_sub_f32_e32 v158, v134, v136
	v_mov_b32_e32 v161, v132
	v_mov_b32_e32 v160, v130
